# code placement: GEMM main K-loop bodies shifted by 4 bytes (back to the baseline phase)
# baseline (speedup 1.0000x reference)
.LBB0_224:
	s_or_b64 exec, exec, s[6:7]
	s_add_i32 s37, s27, 0x18000
	s_or_b32 s6, s9, 0x80
	s_mov_b32 m0, s37
	s_add_i32 s38, s27, 0x1a000
	s_waitcnt vmcnt(4)
	s_barrier
	buffer_load_dwordx4 v140, s[44:47], s6 offen lds
	s_mov_b32 m0, s38
	s_add_i32 s39, s27, 0x8000
	buffer_load_dwordx4 v141, s[44:47], s6 offen lds
	s_or_b32 s6, s8, 0x80
	s_mov_b32 m0, s39
	s_add_i32 s62, s27, 0xa000
	buffer_load_dwordx4 v140, s[48:51], s6 offen lds
	s_mov_b32 m0, s62
	s_add_i32 s63, s27, 0x1c000
	buffer_load_dwordx4 v141, s[48:51], s6 offen lds
	s_or_b32 s6, s9, 0x80080
	s_mov_b32 m0, s63
	s_add_i32 s66, s27, 0x1e000
	buffer_load_dwordx4 v140, s[44:47], s6 offen lds
	s_mov_b32 m0, s66
	v_mov_b32_e32 v0, 0
	buffer_load_dwordx4 v141, s[44:47], s6 offen lds
	s_waitcnt vmcnt(6)
	s_add_i32 s7, s27, 0xc000
	s_add_i32 s6, s27, 0xe000
	s_mov_b32 s67, -2
	s_mov_b32 s68, 0
	v_mov_b32_e32 v1, v0
	v_mov_b32_e32 v2, v0
	v_mov_b32_e32 v3, v0
	v_mov_b32_e32 v4, v0
	v_mov_b32_e32 v5, v0
	v_mov_b32_e32 v6, v0
	v_mov_b32_e32 v7, v0
	v_mov_b32_e32 v8, v0
	v_mov_b32_e32 v9, v0
	v_mov_b32_e32 v10, v0
	v_mov_b32_e32 v11, v0
	v_mov_b32_e32 v12, v0
	v_mov_b32_e32 v13, v0
	v_mov_b32_e32 v14, v0
	v_mov_b32_e32 v15, v0
	v_mov_b32_e32 v18, v0
	v_mov_b32_e32 v19, v0
	v_mov_b32_e32 v20, v0
	v_mov_b32_e32 v21, v0
	v_mov_b32_e32 v22, v0
	v_mov_b32_e32 v23, v0
	v_mov_b32_e32 v24, v0
	v_mov_b32_e32 v25, v0
	v_mov_b32_e32 v26, v0
	v_mov_b32_e32 v27, v0
	v_mov_b32_e32 v28, v0
	v_mov_b32_e32 v29, v0
	v_mov_b32_e32 v30, v0
	v_mov_b32_e32 v31, v0
	v_mov_b32_e32 v32, v0
	v_mov_b32_e32 v33, v0
	v_mov_b32_e32 v34, v0
	v_mov_b32_e32 v35, v0
	v_mov_b32_e32 v36, v0
	v_mov_b32_e32 v37, v0
	v_mov_b32_e32 v38, v0
	v_mov_b32_e32 v39, v0
	v_mov_b32_e32 v40, v0
	v_mov_b32_e32 v41, v0
	v_mov_b32_e32 v42, v0
	v_mov_b32_e32 v43, v0
	v_mov_b32_e32 v44, v0
	v_mov_b32_e32 v45, v0
	v_mov_b32_e32 v46, v0
	v_mov_b32_e32 v47, v0
	v_mov_b32_e32 v48, v0
	v_mov_b32_e32 v49, v0
	v_mov_b32_e32 v50, v0
	v_mov_b32_e32 v51, v0
	v_mov_b32_e32 v52, v0
	v_mov_b32_e32 v53, v0
	v_mov_b32_e32 v54, v0
	v_mov_b32_e32 v55, v0
	v_mov_b32_e32 v56, v0
	v_mov_b32_e32 v57, v0
	v_mov_b32_e32 v58, v0
	v_mov_b32_e32 v59, v0
	v_mov_b32_e32 v60, v0
	v_mov_b32_e32 v61, v0
	v_mov_b32_e32 v62, v0
	v_mov_b32_e32 v63, v0
	v_mov_b32_e32 v64, v0
	v_mov_b32_e32 v65, v0
	v_mov_b32_e32 v66, v0
	v_mov_b32_e32 v67, v0
	v_mov_b32_e32 v68, v0
	v_mov_b32_e32 v69, v0
	v_mov_b32_e32 v70, v0
	v_mov_b32_e32 v71, v0
	v_mov_b32_e32 v72, v0
	v_mov_b32_e32 v73, v0
	v_mov_b32_e32 v74, v0
	v_mov_b32_e32 v75, v0
	v_mov_b32_e32 v76, v0
	v_mov_b32_e32 v77, v0
	v_mov_b32_e32 v78, v0
	v_mov_b32_e32 v79, v0
	v_mov_b32_e32 v80, v0
	v_mov_b32_e32 v81, v0
	v_mov_b32_e32 v82, v0
	v_mov_b32_e32 v83, v0
	v_mov_b32_e32 v84, v0
	v_mov_b32_e32 v85, v0
	v_mov_b32_e32 v86, v0
	v_mov_b32_e32 v87, v0
	v_mov_b32_e32 v88, v0
	v_mov_b32_e32 v89, v0
	v_mov_b32_e32 v90, v0
	v_mov_b32_e32 v91, v0
	v_mov_b32_e32 v92, v0
	v_mov_b32_e32 v93, v0
	v_mov_b32_e32 v94, v0
	v_mov_b32_e32 v95, v0
	v_mov_b32_e32 v96, v0
	v_mov_b32_e32 v97, v0
	v_mov_b32_e32 v98, v0
	v_mov_b32_e32 v99, v0
	v_mov_b32_e32 v100, v0
	v_mov_b32_e32 v101, v0
	v_mov_b32_e32 v102, v0
	v_mov_b32_e32 v103, v0
	v_mov_b32_e32 v104, v0
	v_mov_b32_e32 v105, v0
	v_mov_b32_e32 v106, v0
	v_mov_b32_e32 v107, v0
	v_mov_b32_e32 v108, v0
	v_mov_b32_e32 v109, v0
	v_mov_b32_e32 v110, v0
	v_mov_b32_e32 v111, v0
	v_mov_b32_e32 v112, v0
	v_mov_b32_e32 v113, v0
	v_mov_b32_e32 v114, v0
	v_mov_b32_e32 v115, v0
	v_mov_b32_e32 v116, v0
	v_mov_b32_e32 v117, v0
	v_mov_b32_e32 v118, v0
	v_mov_b32_e32 v119, v0
	v_mov_b32_e32 v120, v0
	v_mov_b32_e32 v121, v0
	v_mov_b32_e32 v122, v0
	v_mov_b32_e32 v123, v0
	v_mov_b32_e32 v124, v0
	v_mov_b32_e32 v125, v0
	v_mov_b32_e32 v126, v0
	v_mov_b32_e32 v127, v0
	v_mov_b32_e32 v128, v0
	v_mov_b32_e32 v129, v0
	s_barrier
	s_nop 0
.LBB0_225:
	ds_read_b128 v[132:135], v142
	ds_read_b128 v[136:139], v142 offset:1024
	ds_read_b128 v[150:153], v142 offset:2048
	ds_read_b128 v[154:157], v142 offset:3072
	s_add_i32 s69, s8, s68
	s_add_i32 s70, s69, 0x80080
	s_mov_b32 m0, s7
	ds_read_b128 v[158:161], v143
	ds_read_b128 v[162:165], v143 offset:1024
	ds_read_b128 v[166:169], v144
	ds_read_b128 v[170:173], v144 offset:1024
	ds_read_b128 v[178:181], v145
	ds_read_b128 v[214:217], v145 offset:1024
	ds_read_b128 v[218:221], v146
	ds_read_b128 v[222:225], v146 offset:1024
	buffer_load_dwordx4 v140, s[48:51], s70 offen lds
	s_mov_b32 m0, s6
	s_nop 0
	buffer_load_dwordx4 v141, s[48:51], s70 offen lds
	s_waitcnt lgkmcnt(8)
	s_barrier
	s_waitcnt lgkmcnt(0)
	s_setprio 1
	s_waitcnt lgkmcnt(0)
	v_mfma_f32_16x16x32_bf16 v[126:129], v[132:135], v[158:161], v[126:129]
	v_mfma_f32_16x16x32_bf16 v[122:125], v[150:153], v[158:161], v[122:125]
	v_mfma_f32_16x16x32_bf16 v[118:121], v[132:135], v[166:169], v[118:121]
	v_mfma_f32_16x16x32_bf16 v[114:117], v[150:153], v[166:169], v[114:117]
	v_mfma_f32_16x16x32_bf16 v[110:113], v[132:135], v[178:181], v[110:113]
	v_mfma_f32_16x16x32_bf16 v[106:109], v[150:153], v[178:181], v[106:109]
	v_mfma_f32_16x16x32_bf16 v[102:105], v[132:135], v[218:221], v[102:105]
	v_mfma_f32_16x16x32_bf16 v[98:101], v[150:153], v[218:221], v[98:101]
	v_mfma_f32_16x16x32_bf16 v[126:129], v[136:139], v[162:165], v[126:129]
	v_mfma_f32_16x16x32_bf16 v[122:125], v[154:157], v[162:165], v[122:125]
	v_mfma_f32_16x16x32_bf16 v[118:121], v[136:139], v[170:173], v[118:121]
	v_mfma_f32_16x16x32_bf16 v[114:117], v[154:157], v[170:173], v[114:117]
	v_mfma_f32_16x16x32_bf16 v[110:113], v[136:139], v[214:217], v[110:113]
	v_mfma_f32_16x16x32_bf16 v[106:109], v[154:157], v[214:217], v[106:109]
	v_mfma_f32_16x16x32_bf16 v[102:105], v[136:139], v[222:225], v[102:105]
	v_mfma_f32_16x16x32_bf16 v[98:101], v[154:157], v[222:225], v[98:101]
	s_setprio 0
	s_barrier
	s_add_i32 s70, s9, s68
	s_add_i32 s71, s70, 0x100
	s_mov_b32 m0, s28
	ds_read_b128 v[226:229], v147
	ds_read_b128 v[230:233], v147 offset:1024
	ds_read_b128 v[234:237], v147 offset:2048
	ds_read_b128 v[238:241], v147 offset:3072
	buffer_load_dwordx4 v140, s[44:47], s71 offen lds
	s_mov_b32 m0, s29
	s_nop 0
	buffer_load_dwordx4 v141, s[44:47], s71 offen lds
	s_barrier
	s_waitcnt lgkmcnt(0)
	s_setprio 1
	s_waitcnt lgkmcnt(0)
	v_mfma_f32_16x16x32_bf16 v[94:97], v[226:229], v[158:161], v[94:97]
	v_mfma_f32_16x16x32_bf16 v[90:93], v[234:237], v[158:161], v[90:93]
	v_mfma_f32_16x16x32_bf16 v[86:89], v[226:229], v[166:169], v[86:89]
	v_mfma_f32_16x16x32_bf16 v[82:85], v[234:237], v[166:169], v[82:85]
	v_mfma_f32_16x16x32_bf16 v[78:81], v[226:229], v[178:181], v[78:81]
	v_mfma_f32_16x16x32_bf16 v[74:77], v[234:237], v[178:181], v[74:77]
	v_mfma_f32_16x16x32_bf16 v[70:73], v[226:229], v[218:221], v[70:73]
	v_mfma_f32_16x16x32_bf16 v[66:69], v[234:237], v[218:221], v[66:69]
	v_mfma_f32_16x16x32_bf16 v[94:97], v[230:233], v[162:165], v[94:97]
	v_mfma_f32_16x16x32_bf16 v[90:93], v[238:241], v[162:165], v[90:93]
	v_mfma_f32_16x16x32_bf16 v[86:89], v[230:233], v[170:173], v[86:89]
	v_mfma_f32_16x16x32_bf16 v[82:85], v[238:241], v[170:173], v[82:85]
	v_mfma_f32_16x16x32_bf16 v[78:81], v[230:233], v[214:217], v[78:81]
	v_mfma_f32_16x16x32_bf16 v[74:77], v[238:241], v[214:217], v[74:77]
	v_mfma_f32_16x16x32_bf16 v[70:73], v[230:233], v[222:225], v[70:73]
	v_mfma_f32_16x16x32_bf16 v[66:69], v[238:241], v[222:225], v[66:69]
	s_setprio 0
	s_add_i32 s71, s69, 0x100
	s_mov_b32 m0, s27
	s_barrier
	ds_read_b128 v[158:161], v143 offset:16384
	ds_read_b128 v[162:165], v143 offset:17408
	ds_read_b128 v[166:169], v144 offset:16384
	ds_read_b128 v[170:173], v144 offset:17408
	ds_read_b128 v[178:181], v145 offset:16384
	ds_read_b128 v[214:217], v145 offset:17408
	ds_read_b128 v[218:221], v146 offset:16384
	ds_read_b128 v[222:225], v146 offset:17408
	buffer_load_dwordx4 v140, s[48:51], s71 offen lds
	s_mov_b32 m0, s30
	s_nop 0
	buffer_load_dwordx4 v141, s[48:51], s71 offen lds
	s_barrier
	s_waitcnt lgkmcnt(0)
	s_setprio 1
	s_waitcnt lgkmcnt(0)
	v_mfma_f32_16x16x32_bf16 v[62:65], v[132:135], v[158:161], v[62:65]
	v_mfma_f32_16x16x32_bf16 v[58:61], v[150:153], v[158:161], v[58:61]
	v_mfma_f32_16x16x32_bf16 v[54:57], v[132:135], v[166:169], v[54:57]
	v_mfma_f32_16x16x32_bf16 v[50:53], v[150:153], v[166:169], v[50:53]
	v_mfma_f32_16x16x32_bf16 v[46:49], v[132:135], v[178:181], v[46:49]
	v_mfma_f32_16x16x32_bf16 v[42:45], v[150:153], v[178:181], v[42:45]
	v_mfma_f32_16x16x32_bf16 v[38:41], v[132:135], v[218:221], v[38:41]
	v_mfma_f32_16x16x32_bf16 v[34:37], v[150:153], v[218:221], v[34:37]
	v_mfma_f32_16x16x32_bf16 v[62:65], v[136:139], v[162:165], v[62:65]
	v_mfma_f32_16x16x32_bf16 v[58:61], v[154:157], v[162:165], v[58:61]
	v_mfma_f32_16x16x32_bf16 v[54:57], v[136:139], v[170:173], v[54:57]
	v_mfma_f32_16x16x32_bf16 v[50:53], v[154:157], v[170:173], v[50:53]
	v_mfma_f32_16x16x32_bf16 v[46:49], v[136:139], v[214:217], v[46:49]
	v_mfma_f32_16x16x32_bf16 v[42:45], v[154:157], v[214:217], v[42:45]
	v_mfma_f32_16x16x32_bf16 v[38:41], v[136:139], v[222:225], v[38:41]
	v_mfma_f32_16x16x32_bf16 v[34:37], v[154:157], v[222:225], v[34:37]
	s_setprio 0
	s_barrier
	s_add_i32 s71, s70, 0x80100
	s_mov_b32 m0, s31
	s_nop 0
	buffer_load_dwordx4 v140, s[44:47], s71 offen lds
	s_mov_b32 m0, s34
	s_nop 0
	buffer_load_dwordx4 v141, s[44:47], s71 offen lds
	s_waitcnt vmcnt(6)
	s_barrier
	s_setprio 1
	v_mfma_f32_16x16x32_bf16 v[30:33], v[226:229], v[158:161], v[30:33]
	v_mfma_f32_16x16x32_bf16 v[26:29], v[234:237], v[158:161], v[26:29]
	v_mfma_f32_16x16x32_bf16 v[22:25], v[226:229], v[166:169], v[22:25]
	v_mfma_f32_16x16x32_bf16 v[18:21], v[234:237], v[166:169], v[18:21]
	v_mfma_f32_16x16x32_bf16 v[12:15], v[226:229], v[178:181], v[12:15]
	v_mfma_f32_16x16x32_bf16 v[8:11], v[234:237], v[178:181], v[8:11]
	v_mfma_f32_16x16x32_bf16 v[4:7], v[226:229], v[218:221], v[4:7]
	v_mfma_f32_16x16x32_bf16 v[0:3], v[234:237], v[218:221], v[0:3]
	v_mfma_f32_16x16x32_bf16 v[30:33], v[230:233], v[162:165], v[30:33]
	v_mfma_f32_16x16x32_bf16 v[26:29], v[238:241], v[162:165], v[26:29]
	v_mfma_f32_16x16x32_bf16 v[22:25], v[230:233], v[170:173], v[22:25]
	v_mfma_f32_16x16x32_bf16 v[18:21], v[238:241], v[170:173], v[18:21]
	v_mfma_f32_16x16x32_bf16 v[12:15], v[230:233], v[214:217], v[12:15]
	v_mfma_f32_16x16x32_bf16 v[8:11], v[238:241], v[214:217], v[8:11]
	v_mfma_f32_16x16x32_bf16 v[4:7], v[230:233], v[222:225], v[4:7]
	v_mfma_f32_16x16x32_bf16 v[0:3], v[238:241], v[222:225], v[0:3]
	s_setprio 0
	s_barrier
	ds_read_b128 v[132:135], v148
	ds_read_b128 v[136:139], v148 offset:1024
	ds_read_b128 v[150:153], v148 offset:2048
	ds_read_b128 v[154:157], v148 offset:3072
	s_add_i32 s71, s69, 0x80100
	s_mov_b32 m0, s35
	ds_read_b128 v[158:161], v143 offset:32768
	ds_read_b128 v[162:165], v143 offset:33792
	ds_read_b128 v[166:169], v144 offset:32768
	ds_read_b128 v[170:173], v144 offset:33792
	ds_read_b128 v[178:181], v145 offset:32768
	ds_read_b128 v[214:217], v145 offset:33792
	ds_read_b128 v[218:221], v146 offset:32768
	ds_read_b128 v[222:225], v146 offset:33792
	buffer_load_dwordx4 v140, s[48:51], s71 offen lds
	s_mov_b32 m0, s36
	s_nop 0
	buffer_load_dwordx4 v141, s[48:51], s71 offen lds
	s_waitcnt lgkmcnt(8)
	s_barrier
	s_waitcnt lgkmcnt(0)
	s_setprio 1
	s_waitcnt lgkmcnt(0)
	v_mfma_f32_16x16x32_bf16 v[126:129], v[132:135], v[158:161], v[126:129]
	v_mfma_f32_16x16x32_bf16 v[122:125], v[150:153], v[158:161], v[122:125]
	v_mfma_f32_16x16x32_bf16 v[118:121], v[132:135], v[166:169], v[118:121]
	v_mfma_f32_16x16x32_bf16 v[114:117], v[150:153], v[166:169], v[114:117]
	v_mfma_f32_16x16x32_bf16 v[110:113], v[132:135], v[178:181], v[110:113]
	v_mfma_f32_16x16x32_bf16 v[106:109], v[150:153], v[178:181], v[106:109]
	v_mfma_f32_16x16x32_bf16 v[102:105], v[132:135], v[218:221], v[102:105]
	v_mfma_f32_16x16x32_bf16 v[98:101], v[150:153], v[218:221], v[98:101]
	v_mfma_f32_16x16x32_bf16 v[126:129], v[136:139], v[162:165], v[126:129]
	v_mfma_f32_16x16x32_bf16 v[122:125], v[154:157], v[162:165], v[122:125]
	v_mfma_f32_16x16x32_bf16 v[118:121], v[136:139], v[170:173], v[118:121]
	v_mfma_f32_16x16x32_bf16 v[114:117], v[154:157], v[170:173], v[114:117]
	v_mfma_f32_16x16x32_bf16 v[110:113], v[136:139], v[214:217], v[110:113]
	v_mfma_f32_16x16x32_bf16 v[106:109], v[154:157], v[214:217], v[106:109]
	v_mfma_f32_16x16x32_bf16 v[102:105], v[136:139], v[222:225], v[102:105]
	v_mfma_f32_16x16x32_bf16 v[98:101], v[154:157], v[222:225], v[98:101]
	s_setprio 0
	s_barrier
	s_add_i32 s71, s70, 0x180
	s_mov_b32 m0, s37
	ds_read_b128 v[226:229], v149
	ds_read_b128 v[230:233], v149 offset:1024
	ds_read_b128 v[234:237], v149 offset:2048
	ds_read_b128 v[238:241], v149 offset:3072
	buffer_load_dwordx4 v140, s[44:47], s71 offen lds
	s_mov_b32 m0, s38
	s_nop 0
	buffer_load_dwordx4 v141, s[44:47], s71 offen lds
	s_barrier
	s_waitcnt lgkmcnt(0)
	s_setprio 1
	s_waitcnt lgkmcnt(0)
	v_mfma_f32_16x16x32_bf16 v[94:97], v[226:229], v[158:161], v[94:97]
	v_mfma_f32_16x16x32_bf16 v[90:93], v[234:237], v[158:161], v[90:93]
	v_mfma_f32_16x16x32_bf16 v[86:89], v[226:229], v[166:169], v[86:89]
	v_mfma_f32_16x16x32_bf16 v[82:85], v[234:237], v[166:169], v[82:85]
	v_mfma_f32_16x16x32_bf16 v[78:81], v[226:229], v[178:181], v[78:81]
	v_mfma_f32_16x16x32_bf16 v[74:77], v[234:237], v[178:181], v[74:77]
	v_mfma_f32_16x16x32_bf16 v[70:73], v[226:229], v[218:221], v[70:73]
	v_mfma_f32_16x16x32_bf16 v[66:69], v[234:237], v[218:221], v[66:69]
	v_mfma_f32_16x16x32_bf16 v[94:97], v[230:233], v[162:165], v[94:97]
	v_mfma_f32_16x16x32_bf16 v[90:93], v[238:241], v[162:165], v[90:93]
	v_mfma_f32_16x16x32_bf16 v[86:89], v[230:233], v[170:173], v[86:89]
	v_mfma_f32_16x16x32_bf16 v[82:85], v[238:241], v[170:173], v[82:85]
	v_mfma_f32_16x16x32_bf16 v[78:81], v[230:233], v[214:217], v[78:81]
	v_mfma_f32_16x16x32_bf16 v[74:77], v[238:241], v[214:217], v[74:77]
	v_mfma_f32_16x16x32_bf16 v[70:73], v[230:233], v[222:225], v[70:73]
	v_mfma_f32_16x16x32_bf16 v[66:69], v[238:241], v[222:225], v[66:69]
	s_setprio 0
	s_addk_i32 s69, 0x180
	s_mov_b32 m0, s39
	s_barrier
	ds_read_b128 v[158:161], v143 offset:49152
	ds_read_b128 v[162:165], v143 offset:50176
	ds_read_b128 v[166:169], v144 offset:49152
	ds_read_b128 v[170:173], v144 offset:50176
	ds_read_b128 v[178:181], v145 offset:49152
	ds_read_b128 v[214:217], v145 offset:50176
	ds_read_b128 v[218:221], v146 offset:49152
	ds_read_b128 v[222:225], v146 offset:50176
	buffer_load_dwordx4 v140, s[48:51], s69 offen lds
	s_mov_b32 m0, s62
	s_nop 0
	buffer_load_dwordx4 v141, s[48:51], s69 offen lds
	s_barrier
	s_waitcnt lgkmcnt(0)
	s_setprio 1
	s_waitcnt lgkmcnt(0)
	v_mfma_f32_16x16x32_bf16 v[62:65], v[132:135], v[158:161], v[62:65]
	v_mfma_f32_16x16x32_bf16 v[58:61], v[150:153], v[158:161], v[58:61]
	v_mfma_f32_16x16x32_bf16 v[54:57], v[132:135], v[166:169], v[54:57]
	v_mfma_f32_16x16x32_bf16 v[50:53], v[150:153], v[166:169], v[50:53]
	v_mfma_f32_16x16x32_bf16 v[46:49], v[132:135], v[178:181], v[46:49]
	v_mfma_f32_16x16x32_bf16 v[42:45], v[150:153], v[178:181], v[42:45]
	v_mfma_f32_16x16x32_bf16 v[38:41], v[132:135], v[218:221], v[38:41]
	v_mfma_f32_16x16x32_bf16 v[34:37], v[150:153], v[218:221], v[34:37]
	v_mfma_f32_16x16x32_bf16 v[62:65], v[136:139], v[162:165], v[62:65]
	v_mfma_f32_16x16x32_bf16 v[58:61], v[154:157], v[162:165], v[58:61]
	v_mfma_f32_16x16x32_bf16 v[54:57], v[136:139], v[170:173], v[54:57]
	v_mfma_f32_16x16x32_bf16 v[50:53], v[154:157], v[170:173], v[50:53]
	v_mfma_f32_16x16x32_bf16 v[46:49], v[136:139], v[214:217], v[46:49]
	v_mfma_f32_16x16x32_bf16 v[42:45], v[154:157], v[214:217], v[42:45]
	v_mfma_f32_16x16x32_bf16 v[38:41], v[136:139], v[222:225], v[38:41]
	v_mfma_f32_16x16x32_bf16 v[34:37], v[154:157], v[222:225], v[34:37]
	s_setprio 0
	s_barrier
	s_add_i32 s70, s70, 0x80180
	s_mov_b32 m0, s63
	s_nop 0
	buffer_load_dwordx4 v140, s[44:47], s70 offen lds
	s_mov_b32 m0, s66
	s_nop 0
	buffer_load_dwordx4 v141, s[44:47], s70 offen lds
	s_waitcnt vmcnt(6)
	s_barrier
	s_setprio 1
	v_mfma_f32_16x16x32_bf16 v[30:33], v[226:229], v[158:161], v[30:33]
	v_mfma_f32_16x16x32_bf16 v[26:29], v[234:237], v[158:161], v[26:29]
	v_mfma_f32_16x16x32_bf16 v[22:25], v[226:229], v[166:169], v[22:25]
	v_mfma_f32_16x16x32_bf16 v[18:21], v[234:237], v[166:169], v[18:21]
	v_mfma_f32_16x16x32_bf16 v[12:15], v[226:229], v[178:181], v[12:15]
	v_mfma_f32_16x16x32_bf16 v[8:11], v[234:237], v[178:181], v[8:11]
	v_mfma_f32_16x16x32_bf16 v[4:7], v[226:229], v[218:221], v[4:7]
	v_mfma_f32_16x16x32_bf16 v[0:3], v[234:237], v[218:221], v[0:3]
	v_mfma_f32_16x16x32_bf16 v[30:33], v[230:233], v[162:165], v[30:33]
	v_mfma_f32_16x16x32_bf16 v[26:29], v[238:241], v[162:165], v[26:29]
	v_mfma_f32_16x16x32_bf16 v[22:25], v[230:233], v[170:173], v[22:25]
	v_mfma_f32_16x16x32_bf16 v[18:21], v[238:241], v[170:173], v[18:21]
	v_mfma_f32_16x16x32_bf16 v[12:15], v[230:233], v[214:217], v[12:15]
	v_mfma_f32_16x16x32_bf16 v[8:11], v[238:241], v[214:217], v[8:11]
	v_mfma_f32_16x16x32_bf16 v[4:7], v[230:233], v[222:225], v[4:7]
	v_mfma_f32_16x16x32_bf16 v[0:3], v[238:241], v[222:225], v[0:3]
	s_setprio 0
	s_add_i32 s67, s67, 2
	s_addk_i32 s68, 0x100
	s_cmp_lt_u32 s67, 28
	s_barrier
	s_cbranch_scc1 .LBB0_225
	s_nop 0
	v_mov_b32_e32 v150, v130
	s_or_b32 s8, s8, 0x80f80
	v_and_b32_e32 v158, 15, v150
	v_bfe_u32 v132, v150, 4, 2
	v_lshlrev_b32_e32 v134, 2, v150
	v_bfe_u32 v152, v150, 6, 2
	v_lshlrev_b32_e32 v151, 4, v132
	v_lshlrev_b32_e32 v133, 6, v158
	v_and_b32_e32 v139, 32, v134
	v_lshlrev_b32_e32 v138, 12, v152
	v_bitop3_b32 v153, v151, v139, v133 bitop3:0x36
	v_add3_u32 v133, s78, v153, v138
	ds_read_b128 v[134:137], v133
	ds_read_b128 v[154:157], v133 offset:1024
	ds_read_b128 v[160:163], v133 offset:2048
	ds_read_b128 v[164:167], v133 offset:3072
	v_ashrrev_i32_e32 v133, 2, v150
	v_lshlrev_b32_e32 v172, 6, v150
	v_and_b32_e32 v133, 0xffffffc0, v133
	v_and_b32_e32 v172, 0x3c0, v172
	v_lshlrev_b32_e32 v159, 7, v133
	v_bitop3_b32 v139, v172, v139, v151 bitop3:0x36
	s_waitcnt vmcnt(0)
	v_add3_u32 v176, 0, v153, v159
	v_add3_u32 v139, 0, v139, v159
	s_mov_b32 m0, s7
	ds_read_b128 v[168:171], v176
	ds_read_b128 v[178:181], v176 offset:1024
	ds_read_b128 v[214:217], v139 offset:2048
	ds_read_b128 v[218:221], v139 offset:3072
	ds_read_b128 v[222:225], v139 offset:4096
	ds_read_b128 v[226:229], v139 offset:5120
	ds_read_b128 v[230:233], v139 offset:6144
	ds_read_b128 v[234:237], v139 offset:7168
	buffer_load_dwordx4 v140, s[48:51], s8 offen lds
	s_mov_b32 m0, s6
	s_nop 0
	buffer_load_dwordx4 v141, s[48:51], s8 offen lds
	s_barrier
	s_waitcnt lgkmcnt(0)
	s_setprio 1
	s_waitcnt lgkmcnt(0)
	v_mfma_f32_16x16x32_bf16 v[126:129], v[134:137], v[168:171], v[126:129]
	v_mfma_f32_16x16x32_bf16 v[122:125], v[160:163], v[168:171], v[122:125]
	v_mfma_f32_16x16x32_bf16 v[118:121], v[134:137], v[214:217], v[118:121]
	v_mfma_f32_16x16x32_bf16 v[114:117], v[160:163], v[214:217], v[114:117]
	v_mfma_f32_16x16x32_bf16 v[110:113], v[134:137], v[222:225], v[110:113]
	v_mfma_f32_16x16x32_bf16 v[106:109], v[160:163], v[222:225], v[106:109]
	v_mfma_f32_16x16x32_bf16 v[102:105], v[134:137], v[230:233], v[102:105]
	v_mfma_f32_16x16x32_bf16 v[98:101], v[160:163], v[230:233], v[98:101]
	v_mfma_f32_16x16x32_bf16 v[126:129], v[154:157], v[178:181], v[126:129]
	v_mfma_f32_16x16x32_bf16 v[122:125], v[164:167], v[178:181], v[122:125]
	v_mfma_f32_16x16x32_bf16 v[118:121], v[154:157], v[218:221], v[118:121]
	v_mfma_f32_16x16x32_bf16 v[114:117], v[164:167], v[218:221], v[114:117]
	v_mfma_f32_16x16x32_bf16 v[110:113], v[154:157], v[226:229], v[110:113]
	v_mfma_f32_16x16x32_bf16 v[106:109], v[164:167], v[226:229], v[106:109]
	v_mfma_f32_16x16x32_bf16 v[102:105], v[154:157], v[234:237], v[102:105]
	v_mfma_f32_16x16x32_bf16 v[98:101], v[164:167], v[234:237], v[98:101]
	s_setprio 0
	v_add3_u32 v159, s77, v153, v138
	s_barrier
	ds_read_b128 v[238:241], v159
	ds_read_b128 v[242:245], v159 offset:1024
	ds_read_b128 v[246:249], v159 offset:2048
	ds_read_b128 v[250:253], v159 offset:3072
	s_barrier
	s_waitcnt lgkmcnt(0)
	s_setprio 1
	s_waitcnt lgkmcnt(0)
	v_mfma_f32_16x16x32_bf16 v[94:97], v[238:241], v[168:171], v[94:97]
	v_mfma_f32_16x16x32_bf16 v[182:185], v[242:245], v[178:181], v[94:97]
	v_mfma_f32_16x16x32_bf16 v[90:93], v[246:249], v[168:171], v[90:93]
	v_mfma_f32_16x16x32_bf16 v[86:89], v[238:241], v[214:217], v[86:89]
	v_mfma_f32_16x16x32_bf16 v[82:85], v[246:249], v[214:217], v[82:85]
	v_mfma_f32_16x16x32_bf16 v[78:81], v[238:241], v[222:225], v[78:81]
	v_mfma_f32_16x16x32_bf16 v[74:77], v[246:249], v[222:225], v[74:77]
	v_mfma_f32_16x16x32_bf16 v[70:73], v[238:241], v[230:233], v[70:73]
	v_mfma_f32_16x16x32_bf16 v[66:69], v[246:249], v[230:233], v[66:69]
	v_mfma_f32_16x16x32_bf16 v[168:171], v[250:253], v[178:181], v[90:93]
	v_mfma_f32_16x16x32_bf16 v[178:181], v[242:245], v[218:221], v[86:89]
	v_mfma_f32_16x16x32_bf16 v[214:217], v[250:253], v[218:221], v[82:85]
	v_mfma_f32_16x16x32_bf16 v[218:221], v[242:245], v[226:229], v[78:81]
	v_mfma_f32_16x16x32_bf16 v[222:225], v[250:253], v[226:229], v[74:77]
	v_mfma_f32_16x16x32_bf16 v[226:229], v[242:245], v[234:237], v[70:73]
	v_mfma_f32_16x16x32_bf16 v[230:233], v[250:253], v[234:237], v[66:69]
	s_setprio 0
	s_barrier
	s_nop 0
	ds_read_b128 v[66:69], v176 offset:16384
	ds_read_b128 v[70:73], v176 offset:17408
	ds_read_b128 v[74:77], v139 offset:18432
	ds_read_b128 v[78:81], v139 offset:19456
	ds_read_b128 v[82:85], v139 offset:20480
	ds_read_b128 v[86:89], v139 offset:21504
	ds_read_b128 v[90:93], v139 offset:22528
	ds_read_b128 v[94:97], v139 offset:23552
	s_waitcnt vmcnt(4)
	s_barrier
	s_waitcnt lgkmcnt(0)
	s_setprio 1
	s_waitcnt lgkmcnt(0)
	v_mfma_f32_16x16x32_bf16 v[62:65], v[134:137], v[66:69], v[62:65]
	v_mfma_f32_16x16x32_bf16 v[58:61], v[160:163], v[66:69], v[58:61]
	v_mfma_f32_16x16x32_bf16 v[54:57], v[134:137], v[74:77], v[54:57]
	v_mfma_f32_16x16x32_bf16 v[50:53], v[160:163], v[74:77], v[50:53]
	v_mfma_f32_16x16x32_bf16 v[46:49], v[134:137], v[82:85], v[46:49]
	v_mfma_f32_16x16x32_bf16 v[42:45], v[160:163], v[82:85], v[42:45]
	v_mfma_f32_16x16x32_bf16 v[38:41], v[134:137], v[90:93], v[38:41]
	v_mfma_f32_16x16x32_bf16 v[34:37], v[160:163], v[90:93], v[34:37]
	v_mfma_f32_16x16x32_bf16 v[62:65], v[154:157], v[70:73], v[62:65]
	v_mfma_f32_16x16x32_bf16 v[58:61], v[164:167], v[70:73], v[58:61]
	v_mfma_f32_16x16x32_bf16 v[54:57], v[154:157], v[78:81], v[54:57]
	v_mfma_f32_16x16x32_bf16 v[50:53], v[164:167], v[78:81], v[50:53]
	v_mfma_f32_16x16x32_bf16 v[46:49], v[154:157], v[86:89], v[46:49]
	v_mfma_f32_16x16x32_bf16 v[42:45], v[164:167], v[86:89], v[42:45]
	v_mfma_f32_16x16x32_bf16 v[38:41], v[154:157], v[94:97], v[38:41]
	v_mfma_f32_16x16x32_bf16 v[34:37], v[164:167], v[94:97], v[34:37]
	s_setprio 0
	s_setprio 1
	v_mfma_f32_16x16x32_bf16 v[30:33], v[238:241], v[66:69], v[30:33]
	v_mfma_f32_16x16x32_bf16 v[26:29], v[246:249], v[66:69], v[26:29]
	v_mfma_f32_16x16x32_bf16 v[22:25], v[238:241], v[74:77], v[22:25]
	v_mfma_f32_16x16x32_bf16 v[18:21], v[246:249], v[74:77], v[18:21]
	v_mfma_f32_16x16x32_bf16 v[12:15], v[238:241], v[82:85], v[12:15]
	v_mfma_f32_16x16x32_bf16 v[8:11], v[246:249], v[82:85], v[8:11]
	v_mfma_f32_16x16x32_bf16 v[4:7], v[238:241], v[90:93], v[4:7]
	v_mfma_f32_16x16x32_bf16 v[0:3], v[246:249], v[90:93], v[0:3]
	v_mfma_f32_16x16x32_bf16 v[134:137], v[242:245], v[70:73], v[30:33]
	v_mfma_f32_16x16x32_bf16 v[154:157], v[250:253], v[70:73], v[26:29]
	v_mfma_f32_16x16x32_bf16 v[160:163], v[242:245], v[78:81], v[22:25]
	v_mfma_f32_16x16x32_bf16 v[164:167], v[250:253], v[78:81], v[18:21]
	v_mfma_f32_16x16x32_bf16 v[234:237], v[242:245], v[86:89], v[12:15]
	v_mfma_f32_16x16x32_bf16 v[82:85], v[250:253], v[86:89], v[8:11]
	v_mfma_f32_16x16x32_bf16 v[238:241], v[242:245], v[94:97], v[4:7]
	v_mfma_f32_16x16x32_bf16 v[242:245], v[250:253], v[94:97], v[0:3]
	s_setprio 0
	s_nop 1
	v_add3_u32 v0, s2, v153, v138
	s_barrier
	ds_read_b128 v[246:249], v0
	ds_read_b128 v[250:253], v0 offset:1024
	ds_read_b128 v[200:203], v0 offset:2048
	ds_read_b128 v[172:175], v0 offset:3072
	ds_read_b128 v[4:7], v176 offset:32768
	ds_read_b128 v[8:11], v176 offset:33792
	ds_read_b128 v[12:15], v139 offset:34816
	ds_read_b128 v[18:21], v139 offset:35840
	ds_read_b128 v[22:25], v139 offset:36864
	ds_read_b128 v[26:29], v139 offset:37888
	ds_read_b128 v[30:33], v139 offset:38912
	ds_read_b128 v[208:211], v139 offset:39936
	s_waitcnt vmcnt(2)
	s_barrier
	s_waitcnt lgkmcnt(0)
	s_setprio 1
	s_waitcnt lgkmcnt(0)
	v_mfma_f32_16x16x32_bf16 v[0:3], v[246:249], v[4:7], v[126:129]
	v_mfma_f32_16x16x32_bf16 v[126:129], v[250:253], v[8:11], v[0:3]
	v_mfma_f32_16x16x32_bf16 v[0:3], v[200:203], v[4:7], v[122:125]
	v_mfma_f32_16x16x32_bf16 v[122:125], v[172:175], v[8:11], v[0:3]
	v_mfma_f32_16x16x32_bf16 v[0:3], v[246:249], v[12:15], v[118:121]
	v_mfma_f32_16x16x32_bf16 v[90:93], v[250:253], v[18:21], v[0:3]
	v_mfma_f32_16x16x32_bf16 v[0:3], v[200:203], v[12:15], v[114:117]
	v_mfma_f32_16x16x32_bf16 v[94:97], v[172:175], v[18:21], v[0:3]
	v_mfma_f32_16x16x32_bf16 v[0:3], v[246:249], v[22:25], v[110:113]
	v_mfma_f32_16x16x32_bf16 v[74:77], v[250:253], v[26:29], v[0:3]
	v_mfma_f32_16x16x32_bf16 v[0:3], v[200:203], v[22:25], v[106:109]
	v_mfma_f32_16x16x32_bf16 v[86:89], v[172:175], v[26:29], v[0:3]
	v_mfma_f32_16x16x32_bf16 v[0:3], v[246:249], v[30:33], v[102:105]
	v_mfma_f32_16x16x32_bf16 v[196:199], v[250:253], v[208:211], v[0:3]
	v_mfma_f32_16x16x32_bf16 v[0:3], v[200:203], v[30:33], v[98:101]
	v_mfma_f32_16x16x32_bf16 v[78:81], v[172:175], v[208:211], v[0:3]
	s_setprio 0
	v_add3_u32 v70, s91, v153, v138
	s_barrier
	ds_read_b128 v[204:207], v70
	s_nop 2
	ds_read_b128 v[0:3], v70 offset:1024
	ds_read_b128 v[66:69], v70 offset:2048
	ds_read_b128 v[70:73], v70 offset:3072
	s_waitcnt vmcnt(0)
	s_barrier
	s_waitcnt lgkmcnt(0)
	s_setprio 1
	s_waitcnt lgkmcnt(0)
	v_mfma_f32_16x16x32_bf16 v[98:101], v[204:207], v[4:7], v[182:185]
	v_mfma_f32_16x16x32_bf16 v[4:7], v[66:69], v[4:7], v[168:171]
	v_mfma_f32_16x16x32_bf16 v[98:101], v[0:3], v[8:11], v[98:101]
	v_mfma_f32_16x16x32_bf16 v[102:105], v[70:73], v[8:11], v[4:7]
	v_mfma_f32_16x16x32_bf16 v[8:11], v[204:207], v[12:15], v[178:181]
	v_mfma_f32_16x16x32_bf16 v[12:15], v[66:69], v[12:15], v[214:217]
	v_mfma_f32_16x16x32_bf16 v[8:11], v[0:3], v[18:21], v[8:11]
	v_mfma_f32_16x16x32_bf16 v[12:15], v[70:73], v[18:21], v[12:15]
	v_mfma_f32_16x16x32_bf16 v[18:21], v[204:207], v[22:25], v[218:221]
	v_mfma_f32_16x16x32_bf16 v[22:25], v[66:69], v[22:25], v[222:225]
	v_mfma_f32_16x16x32_bf16 v[18:21], v[0:3], v[26:29], v[18:21]
	v_mfma_f32_16x16x32_bf16 v[22:25], v[70:73], v[26:29], v[22:25]
	v_mfma_f32_16x16x32_bf16 v[26:29], v[204:207], v[30:33], v[226:229]
	v_mfma_f32_16x16x32_bf16 v[30:33], v[66:69], v[30:33], v[230:233]
	v_mfma_f32_16x16x32_bf16 v[26:29], v[0:3], v[208:211], v[26:29]
	v_mfma_f32_16x16x32_bf16 v[30:33], v[70:73], v[208:211], v[30:33]
	s_setprio 0
	s_barrier
	ds_read_b128 v[168:171], v176 offset:49152
	ds_read_b128 v[178:181], v176 offset:50176
	ds_read_b128 v[208:211], v139 offset:51200
	ds_read_b128 v[214:217], v139 offset:52224
	ds_read_b128 v[218:221], v139 offset:53248
	ds_read_b128 v[222:225], v139 offset:54272
	ds_read_b128 v[226:229], v139 offset:55296
	ds_read_b128 v[230:233], v139 offset:56320
	s_barrier
	s_waitcnt lgkmcnt(0)
	s_setprio 1
	s_waitcnt lgkmcnt(0)
	v_mfma_f32_16x16x32_bf16 v[62:65], v[246:249], v[168:171], v[62:65]
	v_mfma_f32_16x16x32_bf16 v[58:61], v[200:203], v[168:171], v[58:61]
	v_mfma_f32_16x16x32_bf16 v[54:57], v[246:249], v[208:211], v[54:57]
	v_mfma_f32_16x16x32_bf16 v[50:53], v[200:203], v[208:211], v[50:53]
	v_mfma_f32_16x16x32_bf16 v[46:49], v[246:249], v[218:221], v[46:49]
	v_mfma_f32_16x16x32_bf16 v[42:45], v[200:203], v[218:221], v[42:45]
	v_mfma_f32_16x16x32_bf16 v[38:41], v[246:249], v[226:229], v[38:41]
	v_mfma_f32_16x16x32_bf16 v[34:37], v[200:203], v[226:229], v[34:37]
	v_mfma_f32_16x16x32_bf16 v[4:7], v[250:253], v[178:181], v[62:65]
	v_mfma_f32_16x16x32_bf16 v[182:185], v[172:175], v[178:181], v[58:61]
	v_mfma_f32_16x16x32_bf16 v[114:117], v[250:253], v[214:217], v[54:57]
	v_mfma_f32_16x16x32_bf16 v[118:121], v[172:175], v[214:217], v[50:53]
	v_mfma_f32_16x16x32_bf16 v[106:109], v[250:253], v[222:225], v[46:49]
	v_mfma_f32_16x16x32_bf16 v[110:113], v[172:175], v[222:225], v[42:45]
	v_mfma_f32_16x16x32_bf16 v[246:249], v[250:253], v[230:233], v[38:41]
	v_mfma_f32_16x16x32_bf16 v[250:253], v[172:175], v[230:233], v[34:37]
	s_setprio 0
	s_setprio 1
	v_mfma_f32_16x16x32_bf16 v[34:37], v[204:207], v[168:171], v[134:137]
	v_mfma_f32_16x16x32_bf16 v[42:45], v[204:207], v[208:211], v[160:163]
	v_mfma_f32_16x16x32_bf16 v[50:53], v[204:207], v[218:221], v[234:237]
	v_mfma_f32_16x16x32_bf16 v[58:61], v[204:207], v[226:229], v[238:241]
	v_mfma_f32_16x16x32_bf16 v[34:37], v[0:3], v[178:181], v[34:37]
	v_mfma_f32_16x16x32_bf16 v[38:41], v[66:69], v[168:171], v[154:157]
	v_mfma_f32_16x16x32_bf16 v[42:45], v[0:3], v[214:217], v[42:45]
	v_mfma_f32_16x16x32_bf16 v[46:49], v[66:69], v[208:211], v[164:167]
	v_mfma_f32_16x16x32_bf16 v[50:53], v[0:3], v[222:225], v[50:53]
	v_mfma_f32_16x16x32_bf16 v[54:57], v[66:69], v[218:221], v[82:85]
	v_mfma_f32_16x16x32_bf16 v[58:61], v[0:3], v[230:233], v[58:61]
	v_mfma_f32_16x16x32_bf16 v[0:3], v[66:69], v[226:229], v[242:245]
	v_mfma_f32_16x16x32_bf16 v[38:41], v[70:73], v[178:181], v[38:41]
	v_mfma_f32_16x16x32_bf16 v[46:49], v[70:73], v[214:217], v[46:49]
	v_mfma_f32_16x16x32_bf16 v[54:57], v[70:73], v[222:225], v[54:57]
	v_mfma_f32_16x16x32_bf16 v[62:65], v[70:73], v[230:233], v[0:3]
	s_setprio 0
	s_movk_i32 s0, 0x100
	v_cmp_gt_u32_e32 vcc, s0, v150
	s_barrier
	s_and_saveexec_b64 s[6:7], vcc
	s_cbranch_execz .LBB0_228
	s_barrier

.LBB0_525:
	s_or_b64 exec, exec, s[6:7]
	s_add_i32 s25, s17, 0x18000
	s_or_b32 s6, s16, 0x80
	s_mov_b32 m0, s25
	s_add_i32 s26, s17, 0x1a000
	s_waitcnt vmcnt(4)
	s_barrier
	buffer_load_dwordx4 v134, s[52:55], s6 offen lds
	s_mov_b32 m0, s26
	s_add_i32 s27, s17, 0x8000
	buffer_load_dwordx4 v135, s[52:55], s6 offen lds
	s_or_b32 s6, s15, 0x80
	s_mov_b32 m0, s27
	s_add_i32 s28, s17, 0xa000
	buffer_load_dwordx4 v134, s[48:51], s6 offen lds
	s_mov_b32 m0, s28
	s_add_i32 s29, s17, 0x1c000
	buffer_load_dwordx4 v135, s[48:51], s6 offen lds
	s_or_b32 s6, s16, 0x80080
	s_mov_b32 m0, s29
	s_add_i32 s30, s17, 0x1e000
	buffer_load_dwordx4 v134, s[52:55], s6 offen lds
	s_mov_b32 m0, s30
	v_mov_b32_e32 v0, 0
	buffer_load_dwordx4 v135, s[52:55], s6 offen lds
	s_waitcnt vmcnt(6)
	s_add_i32 s7, s17, 0xc000
	s_add_i32 s6, s17, 0xe000
	s_mov_b32 s31, -2
	s_mov_b32 s34, 0
	v_mov_b32_e32 v1, v0
	v_mov_b32_e32 v2, v0
	v_mov_b32_e32 v3, v0
	v_mov_b32_e32 v4, v0
	v_mov_b32_e32 v5, v0
	v_mov_b32_e32 v6, v0
	v_mov_b32_e32 v7, v0
	v_mov_b32_e32 v8, v0
	v_mov_b32_e32 v9, v0
	v_mov_b32_e32 v10, v0
	v_mov_b32_e32 v11, v0
	v_mov_b32_e32 v12, v0
	v_mov_b32_e32 v13, v0
	v_mov_b32_e32 v14, v0
	v_mov_b32_e32 v15, v0
	v_mov_b32_e32 v18, v0
	v_mov_b32_e32 v19, v0
	v_mov_b32_e32 v20, v0
	v_mov_b32_e32 v21, v0
	v_mov_b32_e32 v22, v0
	v_mov_b32_e32 v23, v0
	v_mov_b32_e32 v24, v0
	v_mov_b32_e32 v25, v0
	v_mov_b32_e32 v26, v0
	v_mov_b32_e32 v27, v0
	v_mov_b32_e32 v28, v0
	v_mov_b32_e32 v29, v0
	v_mov_b32_e32 v30, v0
	v_mov_b32_e32 v31, v0
	v_mov_b32_e32 v32, v0
	v_mov_b32_e32 v33, v0
	v_mov_b32_e32 v34, v0
	v_mov_b32_e32 v35, v0
	v_mov_b32_e32 v36, v0
	v_mov_b32_e32 v37, v0
	v_mov_b32_e32 v38, v0
	v_mov_b32_e32 v39, v0
	v_mov_b32_e32 v40, v0
	v_mov_b32_e32 v41, v0
	v_mov_b32_e32 v42, v0
	v_mov_b32_e32 v43, v0
	v_mov_b32_e32 v44, v0
	v_mov_b32_e32 v45, v0
	v_mov_b32_e32 v46, v0
	v_mov_b32_e32 v47, v0
	v_mov_b32_e32 v48, v0
	v_mov_b32_e32 v49, v0
	v_mov_b32_e32 v50, v0
	v_mov_b32_e32 v51, v0
	v_mov_b32_e32 v52, v0
	v_mov_b32_e32 v53, v0
	v_mov_b32_e32 v54, v0
	v_mov_b32_e32 v55, v0
	v_mov_b32_e32 v56, v0
	v_mov_b32_e32 v57, v0
	v_mov_b32_e32 v58, v0
	v_mov_b32_e32 v59, v0
	v_mov_b32_e32 v60, v0
	v_mov_b32_e32 v61, v0
	v_mov_b32_e32 v62, v0
	v_mov_b32_e32 v63, v0
	v_mov_b32_e32 v64, v0
	v_mov_b32_e32 v65, v0
	v_mov_b32_e32 v66, v0
	v_mov_b32_e32 v67, v0
	v_mov_b32_e32 v68, v0
	v_mov_b32_e32 v69, v0
	v_mov_b32_e32 v70, v0
	v_mov_b32_e32 v71, v0
	v_mov_b32_e32 v72, v0
	v_mov_b32_e32 v73, v0
	v_mov_b32_e32 v74, v0
	v_mov_b32_e32 v75, v0
	v_mov_b32_e32 v76, v0
	v_mov_b32_e32 v77, v0
	v_mov_b32_e32 v78, v0
	v_mov_b32_e32 v79, v0
	v_mov_b32_e32 v80, v0
	v_mov_b32_e32 v81, v0
	v_mov_b32_e32 v82, v0
	v_mov_b32_e32 v83, v0
	v_mov_b32_e32 v84, v0
	v_mov_b32_e32 v85, v0
	v_mov_b32_e32 v86, v0
	v_mov_b32_e32 v87, v0
	v_mov_b32_e32 v88, v0
	v_mov_b32_e32 v89, v0
	v_mov_b32_e32 v90, v0
	v_mov_b32_e32 v91, v0
	v_mov_b32_e32 v92, v0
	v_mov_b32_e32 v93, v0
	v_mov_b32_e32 v94, v0
	v_mov_b32_e32 v95, v0
	v_mov_b32_e32 v96, v0
	v_mov_b32_e32 v97, v0
	v_mov_b32_e32 v98, v0
	v_mov_b32_e32 v99, v0
	v_mov_b32_e32 v100, v0
	v_mov_b32_e32 v101, v0
	v_mov_b32_e32 v102, v0
	v_mov_b32_e32 v103, v0
	v_mov_b32_e32 v104, v0
	v_mov_b32_e32 v105, v0
	v_mov_b32_e32 v106, v0
	v_mov_b32_e32 v107, v0
	v_mov_b32_e32 v108, v0
	v_mov_b32_e32 v109, v0
	v_mov_b32_e32 v110, v0
	v_mov_b32_e32 v111, v0
	v_mov_b32_e32 v112, v0
	v_mov_b32_e32 v113, v0
	v_mov_b32_e32 v114, v0
	v_mov_b32_e32 v115, v0
	v_mov_b32_e32 v116, v0
	v_mov_b32_e32 v117, v0
	v_mov_b32_e32 v118, v0
	v_mov_b32_e32 v119, v0
	v_mov_b32_e32 v120, v0
	v_mov_b32_e32 v121, v0
	v_mov_b32_e32 v122, v0
	v_mov_b32_e32 v123, v0
	v_mov_b32_e32 v124, v0
	v_mov_b32_e32 v125, v0
	v_mov_b32_e32 v126, v0
	v_mov_b32_e32 v127, v0
	v_mov_b32_e32 v128, v0
	v_mov_b32_e32 v129, v0
	s_barrier
	s_nop 0
.LBB0_526:
	ds_read_b128 v[144:147], v136
	ds_read_b128 v[148:151], v136 offset:1024
	ds_read_b128 v[152:155], v136 offset:2048
	ds_read_b128 v[156:159], v136 offset:3072
	s_add_i32 s35, s15, s34
	s_add_i32 s36, s35, 0x80080
	s_mov_b32 m0, s7
	ds_read_b128 v[160:163], v137
	ds_read_b128 v[164:167], v137 offset:1024
	ds_read_b128 v[168:171], v138
	ds_read_b128 v[172:175], v138 offset:1024
	ds_read_b128 v[178:181], v139
	ds_read_b128 v[182:185], v139 offset:1024
	ds_read_b128 v[196:199], v140
	ds_read_b128 v[200:203], v140 offset:1024
	buffer_load_dwordx4 v134, s[48:51], s36 offen lds
	s_mov_b32 m0, s6
	s_nop 0
	buffer_load_dwordx4 v135, s[48:51], s36 offen lds
	s_waitcnt lgkmcnt(8)
	s_barrier
	s_waitcnt lgkmcnt(0)
	s_setprio 1
	s_waitcnt lgkmcnt(7)
	v_mfma_f32_16x16x32_bf16 v[126:129], v[144:147], v[160:163], v[126:129]
	v_mfma_f32_16x16x32_bf16 v[122:125], v[152:155], v[160:163], v[122:125]
	s_waitcnt lgkmcnt(5)
	v_mfma_f32_16x16x32_bf16 v[118:121], v[144:147], v[168:171], v[118:121]
	v_mfma_f32_16x16x32_bf16 v[114:117], v[152:155], v[168:171], v[114:117]
	s_waitcnt lgkmcnt(3)
	v_mfma_f32_16x16x32_bf16 v[110:113], v[144:147], v[178:181], v[110:113]
	v_mfma_f32_16x16x32_bf16 v[106:109], v[152:155], v[178:181], v[106:109]
	s_waitcnt lgkmcnt(1)
	v_mfma_f32_16x16x32_bf16 v[102:105], v[144:147], v[196:199], v[102:105]
	v_mfma_f32_16x16x32_bf16 v[98:101], v[152:155], v[196:199], v[98:101]
	v_mfma_f32_16x16x32_bf16 v[126:129], v[148:151], v[164:167], v[126:129]
	v_mfma_f32_16x16x32_bf16 v[122:125], v[156:159], v[164:167], v[122:125]
	v_mfma_f32_16x16x32_bf16 v[118:121], v[148:151], v[172:175], v[118:121]
	v_mfma_f32_16x16x32_bf16 v[114:117], v[156:159], v[172:175], v[114:117]
	v_mfma_f32_16x16x32_bf16 v[110:113], v[148:151], v[182:185], v[110:113]
	v_mfma_f32_16x16x32_bf16 v[106:109], v[156:159], v[182:185], v[106:109]
	s_waitcnt lgkmcnt(0)
	v_mfma_f32_16x16x32_bf16 v[102:105], v[148:151], v[200:203], v[102:105]
	v_mfma_f32_16x16x32_bf16 v[98:101], v[156:159], v[200:203], v[98:101]
	s_setprio 0
	s_barrier
	s_add_i32 s36, s16, s34
	s_add_i32 s37, s36, 0x100
	s_mov_b32 m0, s18
	ds_read_b128 v[204:207], v141
	ds_read_b128 v[208:211], v141 offset:1024
	ds_read_b128 v[214:217], v141 offset:2048
	ds_read_b128 v[218:221], v141 offset:3072
	buffer_load_dwordx4 v134, s[52:55], s37 offen lds
	s_mov_b32 m0, s19
	s_nop 0
	buffer_load_dwordx4 v135, s[52:55], s37 offen lds
	s_barrier
	s_waitcnt lgkmcnt(0)
	s_setprio 1
	s_waitcnt lgkmcnt(3)
	v_mfma_f32_16x16x32_bf16 v[94:97], v[204:207], v[160:163], v[94:97]
	s_waitcnt lgkmcnt(1)
	v_mfma_f32_16x16x32_bf16 v[90:93], v[214:217], v[160:163], v[90:93]
	v_mfma_f32_16x16x32_bf16 v[86:89], v[204:207], v[168:171], v[86:89]
	v_mfma_f32_16x16x32_bf16 v[82:85], v[214:217], v[168:171], v[82:85]
	v_mfma_f32_16x16x32_bf16 v[78:81], v[204:207], v[178:181], v[78:81]
	v_mfma_f32_16x16x32_bf16 v[74:77], v[214:217], v[178:181], v[74:77]
	v_mfma_f32_16x16x32_bf16 v[70:73], v[204:207], v[196:199], v[70:73]
	v_mfma_f32_16x16x32_bf16 v[66:69], v[214:217], v[196:199], v[66:69]
	v_mfma_f32_16x16x32_bf16 v[94:97], v[208:211], v[164:167], v[94:97]
	s_waitcnt lgkmcnt(0)
	v_mfma_f32_16x16x32_bf16 v[90:93], v[218:221], v[164:167], v[90:93]
	v_mfma_f32_16x16x32_bf16 v[86:89], v[208:211], v[172:175], v[86:89]
	v_mfma_f32_16x16x32_bf16 v[82:85], v[218:221], v[172:175], v[82:85]
	v_mfma_f32_16x16x32_bf16 v[78:81], v[208:211], v[182:185], v[78:81]
	v_mfma_f32_16x16x32_bf16 v[74:77], v[218:221], v[182:185], v[74:77]
	v_mfma_f32_16x16x32_bf16 v[70:73], v[208:211], v[200:203], v[70:73]
	v_mfma_f32_16x16x32_bf16 v[66:69], v[218:221], v[200:203], v[66:69]
	s_setprio 0
	s_add_i32 s37, s35, 0x100
	s_mov_b32 m0, s17
	s_barrier
	ds_read_b128 v[160:163], v137 offset:16384
	ds_read_b128 v[164:167], v137 offset:17408
	ds_read_b128 v[168:171], v138 offset:16384
	ds_read_b128 v[172:175], v138 offset:17408
	ds_read_b128 v[178:181], v139 offset:16384
	ds_read_b128 v[182:185], v139 offset:17408
	ds_read_b128 v[196:199], v140 offset:16384
	ds_read_b128 v[200:203], v140 offset:17408
	buffer_load_dwordx4 v134, s[48:51], s37 offen lds
	s_mov_b32 m0, s20
	s_nop 0
	buffer_load_dwordx4 v135, s[48:51], s37 offen lds
	s_barrier
	s_waitcnt lgkmcnt(0)
	s_setprio 1
	s_waitcnt lgkmcnt(7)
	v_mfma_f32_16x16x32_bf16 v[62:65], v[144:147], v[160:163], v[62:65]
	v_mfma_f32_16x16x32_bf16 v[58:61], v[152:155], v[160:163], v[58:61]
	s_waitcnt lgkmcnt(5)
	v_mfma_f32_16x16x32_bf16 v[54:57], v[144:147], v[168:171], v[54:57]
	v_mfma_f32_16x16x32_bf16 v[50:53], v[152:155], v[168:171], v[50:53]
	s_waitcnt lgkmcnt(3)
	v_mfma_f32_16x16x32_bf16 v[46:49], v[144:147], v[178:181], v[46:49]
	v_mfma_f32_16x16x32_bf16 v[42:45], v[152:155], v[178:181], v[42:45]
	s_waitcnt lgkmcnt(1)
	v_mfma_f32_16x16x32_bf16 v[38:41], v[144:147], v[196:199], v[38:41]
	v_mfma_f32_16x16x32_bf16 v[34:37], v[152:155], v[196:199], v[34:37]
	v_mfma_f32_16x16x32_bf16 v[62:65], v[148:151], v[164:167], v[62:65]
	v_mfma_f32_16x16x32_bf16 v[58:61], v[156:159], v[164:167], v[58:61]
	v_mfma_f32_16x16x32_bf16 v[54:57], v[148:151], v[172:175], v[54:57]
	v_mfma_f32_16x16x32_bf16 v[50:53], v[156:159], v[172:175], v[50:53]
	v_mfma_f32_16x16x32_bf16 v[46:49], v[148:151], v[182:185], v[46:49]
	v_mfma_f32_16x16x32_bf16 v[42:45], v[156:159], v[182:185], v[42:45]
	s_waitcnt lgkmcnt(0)
	v_mfma_f32_16x16x32_bf16 v[38:41], v[148:151], v[200:203], v[38:41]
	v_mfma_f32_16x16x32_bf16 v[34:37], v[156:159], v[200:203], v[34:37]
	s_setprio 0
	s_barrier
	s_add_i32 s37, s36, 0x80100
	s_mov_b32 m0, s21
	s_nop 0
	buffer_load_dwordx4 v134, s[52:55], s37 offen lds
	s_mov_b32 m0, s22
	s_nop 0
	buffer_load_dwordx4 v135, s[52:55], s37 offen lds
	s_waitcnt vmcnt(6)
	s_barrier
	s_setprio 1
	v_mfma_f32_16x16x32_bf16 v[30:33], v[204:207], v[160:163], v[30:33]
	v_mfma_f32_16x16x32_bf16 v[26:29], v[214:217], v[160:163], v[26:29]
	v_mfma_f32_16x16x32_bf16 v[22:25], v[204:207], v[168:171], v[22:25]
	v_mfma_f32_16x16x32_bf16 v[18:21], v[214:217], v[168:171], v[18:21]
	v_mfma_f32_16x16x32_bf16 v[12:15], v[204:207], v[178:181], v[12:15]
	v_mfma_f32_16x16x32_bf16 v[8:11], v[214:217], v[178:181], v[8:11]
	v_mfma_f32_16x16x32_bf16 v[4:7], v[204:207], v[196:199], v[4:7]
	v_mfma_f32_16x16x32_bf16 v[0:3], v[214:217], v[196:199], v[0:3]
	v_mfma_f32_16x16x32_bf16 v[30:33], v[208:211], v[164:167], v[30:33]
	v_mfma_f32_16x16x32_bf16 v[26:29], v[218:221], v[164:167], v[26:29]
	v_mfma_f32_16x16x32_bf16 v[22:25], v[208:211], v[172:175], v[22:25]
	v_mfma_f32_16x16x32_bf16 v[18:21], v[218:221], v[172:175], v[18:21]
	v_mfma_f32_16x16x32_bf16 v[12:15], v[208:211], v[182:185], v[12:15]
	v_mfma_f32_16x16x32_bf16 v[8:11], v[218:221], v[182:185], v[8:11]
	v_mfma_f32_16x16x32_bf16 v[4:7], v[208:211], v[200:203], v[4:7]
	v_mfma_f32_16x16x32_bf16 v[0:3], v[218:221], v[200:203], v[0:3]
	s_setprio 0
	s_barrier
	ds_read_b128 v[144:147], v142
	ds_read_b128 v[148:151], v142 offset:1024
	ds_read_b128 v[152:155], v142 offset:2048
	ds_read_b128 v[156:159], v142 offset:3072
	s_add_i32 s37, s35, 0x80100
	s_mov_b32 m0, s23
	ds_read_b128 v[160:163], v137 offset:32768
	ds_read_b128 v[164:167], v137 offset:33792
	ds_read_b128 v[168:171], v138 offset:32768
	ds_read_b128 v[172:175], v138 offset:33792
	ds_read_b128 v[178:181], v139 offset:32768
	ds_read_b128 v[182:185], v139 offset:33792
	ds_read_b128 v[196:199], v140 offset:32768
	ds_read_b128 v[200:203], v140 offset:33792
	buffer_load_dwordx4 v134, s[48:51], s37 offen lds
	s_mov_b32 m0, s24
	s_nop 0
	buffer_load_dwordx4 v135, s[48:51], s37 offen lds
	s_waitcnt lgkmcnt(8)
	s_barrier
	s_waitcnt lgkmcnt(0)
	s_setprio 1
	s_waitcnt lgkmcnt(7)
	v_mfma_f32_16x16x32_bf16 v[126:129], v[144:147], v[160:163], v[126:129]
	v_mfma_f32_16x16x32_bf16 v[122:125], v[152:155], v[160:163], v[122:125]
	s_waitcnt lgkmcnt(5)
	v_mfma_f32_16x16x32_bf16 v[118:121], v[144:147], v[168:171], v[118:121]
	v_mfma_f32_16x16x32_bf16 v[114:117], v[152:155], v[168:171], v[114:117]
	s_waitcnt lgkmcnt(3)
	v_mfma_f32_16x16x32_bf16 v[110:113], v[144:147], v[178:181], v[110:113]
	v_mfma_f32_16x16x32_bf16 v[106:109], v[152:155], v[178:181], v[106:109]
	s_waitcnt lgkmcnt(1)
	v_mfma_f32_16x16x32_bf16 v[102:105], v[144:147], v[196:199], v[102:105]
	v_mfma_f32_16x16x32_bf16 v[98:101], v[152:155], v[196:199], v[98:101]
	v_mfma_f32_16x16x32_bf16 v[126:129], v[148:151], v[164:167], v[126:129]
	v_mfma_f32_16x16x32_bf16 v[122:125], v[156:159], v[164:167], v[122:125]
	v_mfma_f32_16x16x32_bf16 v[118:121], v[148:151], v[172:175], v[118:121]
	v_mfma_f32_16x16x32_bf16 v[114:117], v[156:159], v[172:175], v[114:117]
	v_mfma_f32_16x16x32_bf16 v[110:113], v[148:151], v[182:185], v[110:113]
	v_mfma_f32_16x16x32_bf16 v[106:109], v[156:159], v[182:185], v[106:109]
	s_waitcnt lgkmcnt(0)
	v_mfma_f32_16x16x32_bf16 v[102:105], v[148:151], v[200:203], v[102:105]
	v_mfma_f32_16x16x32_bf16 v[98:101], v[156:159], v[200:203], v[98:101]
	s_setprio 0
	s_barrier
	s_add_i32 s37, s36, 0x180
	s_mov_b32 m0, s25
	ds_read_b128 v[204:207], v143
	ds_read_b128 v[208:211], v143 offset:1024
	ds_read_b128 v[214:217], v143 offset:2048
	ds_read_b128 v[218:221], v143 offset:3072
	buffer_load_dwordx4 v134, s[52:55], s37 offen lds
	s_mov_b32 m0, s26
	s_nop 0
	buffer_load_dwordx4 v135, s[52:55], s37 offen lds
	s_barrier
	s_waitcnt lgkmcnt(0)
	s_setprio 1
	s_waitcnt lgkmcnt(3)
	v_mfma_f32_16x16x32_bf16 v[94:97], v[204:207], v[160:163], v[94:97]
	s_waitcnt lgkmcnt(1)
	v_mfma_f32_16x16x32_bf16 v[90:93], v[214:217], v[160:163], v[90:93]
	v_mfma_f32_16x16x32_bf16 v[86:89], v[204:207], v[168:171], v[86:89]
	v_mfma_f32_16x16x32_bf16 v[82:85], v[214:217], v[168:171], v[82:85]
	v_mfma_f32_16x16x32_bf16 v[78:81], v[204:207], v[178:181], v[78:81]
	v_mfma_f32_16x16x32_bf16 v[74:77], v[214:217], v[178:181], v[74:77]
	v_mfma_f32_16x16x32_bf16 v[70:73], v[204:207], v[196:199], v[70:73]
	v_mfma_f32_16x16x32_bf16 v[66:69], v[214:217], v[196:199], v[66:69]
	v_mfma_f32_16x16x32_bf16 v[94:97], v[208:211], v[164:167], v[94:97]
	s_waitcnt lgkmcnt(0)
	v_mfma_f32_16x16x32_bf16 v[90:93], v[218:221], v[164:167], v[90:93]
	v_mfma_f32_16x16x32_bf16 v[86:89], v[208:211], v[172:175], v[86:89]
	v_mfma_f32_16x16x32_bf16 v[82:85], v[218:221], v[172:175], v[82:85]
	v_mfma_f32_16x16x32_bf16 v[78:81], v[208:211], v[182:185], v[78:81]
	v_mfma_f32_16x16x32_bf16 v[74:77], v[218:221], v[182:185], v[74:77]
	v_mfma_f32_16x16x32_bf16 v[70:73], v[208:211], v[200:203], v[70:73]
	v_mfma_f32_16x16x32_bf16 v[66:69], v[218:221], v[200:203], v[66:69]
	s_setprio 0
	s_addk_i32 s35, 0x180
	s_mov_b32 m0, s27
	s_barrier
	ds_read_b128 v[160:163], v137 offset:49152
	ds_read_b128 v[164:167], v137 offset:50176
	ds_read_b128 v[168:171], v138 offset:49152
	ds_read_b128 v[172:175], v138 offset:50176
	ds_read_b128 v[178:181], v139 offset:49152
	ds_read_b128 v[182:185], v139 offset:50176
	ds_read_b128 v[196:199], v140 offset:49152
	ds_read_b128 v[200:203], v140 offset:50176
	buffer_load_dwordx4 v134, s[48:51], s35 offen lds
	s_mov_b32 m0, s28
	s_nop 0
	buffer_load_dwordx4 v135, s[48:51], s35 offen lds
	s_barrier
	s_waitcnt lgkmcnt(0)
	s_setprio 1
	s_waitcnt lgkmcnt(7)
	v_mfma_f32_16x16x32_bf16 v[62:65], v[144:147], v[160:163], v[62:65]
	v_mfma_f32_16x16x32_bf16 v[58:61], v[152:155], v[160:163], v[58:61]
	s_waitcnt lgkmcnt(5)
	v_mfma_f32_16x16x32_bf16 v[54:57], v[144:147], v[168:171], v[54:57]
	v_mfma_f32_16x16x32_bf16 v[50:53], v[152:155], v[168:171], v[50:53]
	s_waitcnt lgkmcnt(3)
	v_mfma_f32_16x16x32_bf16 v[46:49], v[144:147], v[178:181], v[46:49]
	v_mfma_f32_16x16x32_bf16 v[42:45], v[152:155], v[178:181], v[42:45]
	s_waitcnt lgkmcnt(1)
	v_mfma_f32_16x16x32_bf16 v[38:41], v[144:147], v[196:199], v[38:41]
	v_mfma_f32_16x16x32_bf16 v[34:37], v[152:155], v[196:199], v[34:37]
	v_mfma_f32_16x16x32_bf16 v[62:65], v[148:151], v[164:167], v[62:65]
	v_mfma_f32_16x16x32_bf16 v[58:61], v[156:159], v[164:167], v[58:61]
	v_mfma_f32_16x16x32_bf16 v[54:57], v[148:151], v[172:175], v[54:57]
	v_mfma_f32_16x16x32_bf16 v[50:53], v[156:159], v[172:175], v[50:53]
	v_mfma_f32_16x16x32_bf16 v[46:49], v[148:151], v[182:185], v[46:49]
	v_mfma_f32_16x16x32_bf16 v[42:45], v[156:159], v[182:185], v[42:45]
	s_waitcnt lgkmcnt(0)
	v_mfma_f32_16x16x32_bf16 v[38:41], v[148:151], v[200:203], v[38:41]
	v_mfma_f32_16x16x32_bf16 v[34:37], v[156:159], v[200:203], v[34:37]
	s_setprio 0
	s_barrier
	s_add_i32 s36, s36, 0x80180
	s_mov_b32 m0, s29
	s_nop 0
	buffer_load_dwordx4 v134, s[52:55], s36 offen lds
	s_mov_b32 m0, s30
	s_nop 0
	buffer_load_dwordx4 v135, s[52:55], s36 offen lds
	s_waitcnt vmcnt(6)
	s_barrier
	s_setprio 1
	v_mfma_f32_16x16x32_bf16 v[30:33], v[204:207], v[160:163], v[30:33]
	v_mfma_f32_16x16x32_bf16 v[26:29], v[214:217], v[160:163], v[26:29]
	v_mfma_f32_16x16x32_bf16 v[22:25], v[204:207], v[168:171], v[22:25]
	v_mfma_f32_16x16x32_bf16 v[18:21], v[214:217], v[168:171], v[18:21]
	v_mfma_f32_16x16x32_bf16 v[12:15], v[204:207], v[178:181], v[12:15]
	v_mfma_f32_16x16x32_bf16 v[8:11], v[214:217], v[178:181], v[8:11]
	v_mfma_f32_16x16x32_bf16 v[4:7], v[204:207], v[196:199], v[4:7]
	v_mfma_f32_16x16x32_bf16 v[0:3], v[214:217], v[196:199], v[0:3]
	v_mfma_f32_16x16x32_bf16 v[30:33], v[208:211], v[164:167], v[30:33]
	v_mfma_f32_16x16x32_bf16 v[26:29], v[218:221], v[164:167], v[26:29]
	v_mfma_f32_16x16x32_bf16 v[22:25], v[208:211], v[172:175], v[22:25]
	v_mfma_f32_16x16x32_bf16 v[18:21], v[218:221], v[172:175], v[18:21]
	v_mfma_f32_16x16x32_bf16 v[12:15], v[208:211], v[182:185], v[12:15]
	v_mfma_f32_16x16x32_bf16 v[8:11], v[218:221], v[182:185], v[8:11]
	v_mfma_f32_16x16x32_bf16 v[4:7], v[208:211], v[200:203], v[4:7]
	v_mfma_f32_16x16x32_bf16 v[0:3], v[218:221], v[200:203], v[0:3]
	s_setprio 0
	s_add_i32 s31, s31, 2
	s_addk_i32 s34, 0x100
	s_cmp_lt_u32 s31, 28
	s_barrier
	s_cbranch_scc1 .LBB0_526
	s_nop 0
	v_mov_b32_e32 v144, v130
	s_or_b32 s15, s15, 0x80f80
	v_and_b32_e32 v147, 15, v144
	v_bfe_u32 v146, v144, 4, 2
	v_lshlrev_b32_e32 v150, 2, v144
	v_bfe_u32 v145, v144, 6, 2
	v_lshlrev_b32_e32 v174, 4, v146
	v_lshlrev_b32_e32 v148, 6, v147
	v_and_b32_e32 v175, 32, v150
	v_lshlrev_b32_e32 v149, 12, v145
	v_bitop3_b32 v176, v174, v175, v148 bitop3:0x36
	v_add3_u32 v148, s78, v176, v149
	ds_read_b128 v[150:153], v148
	ds_read_b128 v[154:157], v148 offset:1024
	ds_read_b128 v[158:161], v148 offset:2048
	ds_read_b128 v[162:165], v148 offset:3072
	v_ashrrev_i32_e32 v148, 2, v144
	v_lshlrev_b32_e32 v178, 6, v144
	v_and_b32_e32 v148, 0xffffffc0, v148
	v_and_b32_e32 v178, 0x3c0, v178
	v_lshlrev_b32_e32 v177, 7, v148
	v_bitop3_b32 v174, v178, v175, v174 bitop3:0x36
	s_waitcnt vmcnt(0)
	v_add3_u32 v190, 0, v176, v177
	v_add3_u32 v174, 0, v174, v177
	s_mov_b32 m0, s7
	ds_read_b128 v[166:169], v190
	ds_read_b128 v[170:173], v190 offset:1024
	ds_read_b128 v[178:181], v174 offset:2048
	ds_read_b128 v[182:185], v174 offset:3072
	ds_read_b128 v[196:199], v174 offset:4096
	ds_read_b128 v[200:203], v174 offset:5120
	ds_read_b128 v[204:207], v174 offset:6144
	ds_read_b128 v[208:211], v174 offset:7168
	buffer_load_dwordx4 v134, s[48:51], s15 offen lds
	s_mov_b32 m0, s6
	s_nop 0
	buffer_load_dwordx4 v135, s[48:51], s15 offen lds
	s_barrier
	s_waitcnt lgkmcnt(0)
	s_setprio 1
	s_waitcnt lgkmcnt(7)
	v_mfma_f32_16x16x32_bf16 v[126:129], v[150:153], v[166:169], v[126:129]
	v_mfma_f32_16x16x32_bf16 v[122:125], v[158:161], v[166:169], v[122:125]
	s_waitcnt lgkmcnt(5)
	v_mfma_f32_16x16x32_bf16 v[118:121], v[150:153], v[178:181], v[118:121]
	v_mfma_f32_16x16x32_bf16 v[114:117], v[158:161], v[178:181], v[114:117]
	s_waitcnt lgkmcnt(1)
	v_mfma_f32_16x16x32_bf16 v[102:105], v[150:153], v[204:207], v[102:105]
	v_mfma_f32_16x16x32_bf16 v[98:101], v[158:161], v[204:207], v[98:101]
	v_mfma_f32_16x16x32_bf16 v[126:129], v[154:157], v[170:173], v[126:129]
	v_mfma_f32_16x16x32_bf16 v[122:125], v[162:165], v[170:173], v[122:125]
	v_mfma_f32_16x16x32_bf16 v[118:121], v[154:157], v[182:185], v[118:121]
	v_mfma_f32_16x16x32_bf16 v[114:117], v[162:165], v[182:185], v[114:117]
	v_mfma_f32_16x16x32_bf16 v[110:113], v[150:153], v[196:199], v[110:113]
	v_mfma_f32_16x16x32_bf16 v[106:109], v[158:161], v[196:199], v[106:109]
	s_waitcnt lgkmcnt(0)
	v_mfma_f32_16x16x32_bf16 v[102:105], v[154:157], v[208:211], v[102:105]
	v_mfma_f32_16x16x32_bf16 v[98:101], v[162:165], v[208:211], v[98:101]
	v_mfma_f32_16x16x32_bf16 v[214:217], v[154:157], v[200:203], v[110:113]
	v_mfma_f32_16x16x32_bf16 v[218:221], v[162:165], v[200:203], v[106:109]
	s_setprio 0
	v_add3_u32 v175, s77, v176, v149
	s_barrier
	ds_read_b128 v[106:109], v175
	ds_read_b128 v[110:113], v175 offset:1024
	ds_read_b128 v[222:225], v175 offset:2048
	ds_read_b128 v[226:229], v175 offset:3072
	s_barrier
	s_waitcnt lgkmcnt(0)
	s_setprio 1
	s_waitcnt lgkmcnt(3)
	v_mfma_f32_16x16x32_bf16 v[94:97], v[106:109], v[166:169], v[94:97]
	s_waitcnt lgkmcnt(1)
	v_mfma_f32_16x16x32_bf16 v[82:85], v[222:225], v[178:181], v[82:85]
	v_mfma_f32_16x16x32_bf16 v[78:81], v[106:109], v[196:199], v[78:81]
	v_mfma_f32_16x16x32_bf16 v[74:77], v[222:225], v[196:199], v[74:77]
	v_mfma_f32_16x16x32_bf16 v[70:73], v[106:109], v[204:207], v[70:73]
	v_mfma_f32_16x16x32_bf16 v[66:69], v[222:225], v[204:207], v[66:69]
	v_mfma_f32_16x16x32_bf16 v[94:97], v[110:113], v[170:173], v[94:97]
	v_mfma_f32_16x16x32_bf16 v[90:93], v[222:225], v[166:169], v[90:93]
	v_mfma_f32_16x16x32_bf16 v[86:89], v[106:109], v[178:181], v[86:89]
	s_waitcnt lgkmcnt(0)
	v_mfma_f32_16x16x32_bf16 v[82:85], v[226:229], v[182:185], v[82:85]
	v_mfma_f32_16x16x32_bf16 v[78:81], v[110:113], v[200:203], v[78:81]
	v_mfma_f32_16x16x32_bf16 v[74:77], v[226:229], v[200:203], v[74:77]
	v_mfma_f32_16x16x32_bf16 v[70:73], v[110:113], v[208:211], v[70:73]
	v_mfma_f32_16x16x32_bf16 v[66:69], v[226:229], v[208:211], v[66:69]
	v_mfma_f32_16x16x32_bf16 v[166:169], v[226:229], v[170:173], v[90:93]
	v_mfma_f32_16x16x32_bf16 v[170:173], v[110:113], v[182:185], v[86:89]
	s_setprio 0
	s_barrier
	s_nop 0
	ds_read_b128 v[86:89], v190 offset:16384
	ds_read_b128 v[90:93], v190 offset:17408
	ds_read_b128 v[178:181], v174 offset:18432
	ds_read_b128 v[182:185], v174 offset:19456
	ds_read_b128 v[196:199], v174 offset:20480
	ds_read_b128 v[200:203], v174 offset:21504
	ds_read_b128 v[204:207], v174 offset:22528
	ds_read_b128 v[208:211], v174 offset:23552
	s_waitcnt vmcnt(4)
	s_barrier
	s_waitcnt lgkmcnt(0)
	s_setprio 1
	s_waitcnt lgkmcnt(5)
	v_mfma_f32_16x16x32_bf16 v[54:57], v[150:153], v[178:181], v[54:57]
	v_mfma_f32_16x16x32_bf16 v[50:53], v[158:161], v[178:181], v[50:53]
	v_mfma_f32_16x16x32_bf16 v[62:65], v[150:153], v[86:89], v[62:65]
	v_mfma_f32_16x16x32_bf16 v[58:61], v[158:161], v[86:89], v[58:61]
	s_waitcnt lgkmcnt(4)
	v_mfma_f32_16x16x32_bf16 v[54:57], v[154:157], v[182:185], v[54:57]
	v_mfma_f32_16x16x32_bf16 v[50:53], v[162:165], v[182:185], v[50:53]
	s_waitcnt lgkmcnt(3)
	v_mfma_f32_16x16x32_bf16 v[46:49], v[150:153], v[196:199], v[46:49]
	v_mfma_f32_16x16x32_bf16 v[42:45], v[158:161], v[196:199], v[42:45]
	s_waitcnt lgkmcnt(1)
	v_mfma_f32_16x16x32_bf16 v[38:41], v[150:153], v[204:207], v[38:41]
	v_mfma_f32_16x16x32_bf16 v[34:37], v[158:161], v[204:207], v[34:37]
	v_mfma_f32_16x16x32_bf16 v[230:233], v[154:157], v[90:93], v[62:65]
	v_mfma_f32_16x16x32_bf16 v[234:237], v[162:165], v[90:93], v[58:61]
	v_mfma_f32_16x16x32_bf16 v[238:241], v[154:157], v[200:203], v[46:49]
	v_mfma_f32_16x16x32_bf16 v[242:245], v[162:165], v[200:203], v[42:45]
	s_waitcnt lgkmcnt(0)
	v_mfma_f32_16x16x32_bf16 v[150:153], v[154:157], v[208:211], v[38:41]
	v_mfma_f32_16x16x32_bf16 v[154:157], v[162:165], v[208:211], v[34:37]
	s_setprio 0
	s_setprio 1
	v_mfma_f32_16x16x32_bf16 v[30:33], v[106:109], v[86:89], v[30:33]
	v_mfma_f32_16x16x32_bf16 v[26:29], v[222:225], v[86:89], v[26:29]
	v_mfma_f32_16x16x32_bf16 v[12:15], v[106:109], v[196:199], v[12:15]
	v_mfma_f32_16x16x32_bf16 v[8:11], v[222:225], v[196:199], v[8:11]
	v_mfma_f32_16x16x32_bf16 v[30:33], v[110:113], v[90:93], v[30:33]
	v_mfma_f32_16x16x32_bf16 v[26:29], v[226:229], v[90:93], v[26:29]
	v_mfma_f32_16x16x32_bf16 v[22:25], v[106:109], v[178:181], v[22:25]
	v_mfma_f32_16x16x32_bf16 v[18:21], v[222:225], v[178:181], v[18:21]
	v_mfma_f32_16x16x32_bf16 v[12:15], v[110:113], v[200:203], v[12:15]
	v_mfma_f32_16x16x32_bf16 v[8:11], v[226:229], v[200:203], v[8:11]
	v_mfma_f32_16x16x32_bf16 v[4:7], v[106:109], v[204:207], v[4:7]
	v_mfma_f32_16x16x32_bf16 v[0:3], v[222:225], v[204:207], v[0:3]
	v_mfma_f32_16x16x32_bf16 v[158:161], v[110:113], v[182:185], v[22:25]
	v_mfma_f32_16x16x32_bf16 v[162:165], v[226:229], v[182:185], v[18:21]
	v_mfma_f32_16x16x32_bf16 v[178:181], v[110:113], v[208:211], v[4:7]
	v_mfma_f32_16x16x32_bf16 v[182:185], v[226:229], v[208:211], v[0:3]
	s_setprio 0
	v_add3_u32 v18, s2, v176, v149
	s_barrier
	s_nop 0
	ds_read_b128 v[0:3], v18
	ds_read_b128 v[4:7], v18 offset:1024
	ds_read_b128 v[196:199], v18 offset:2048
	ds_read_b128 v[200:203], v18 offset:3072
	ds_read_b128 v[18:21], v190 offset:32768
	ds_read_b128 v[22:25], v190 offset:33792
	ds_read_b128 v[42:45], v174 offset:34816
	ds_read_b128 v[46:49], v174 offset:35840
	ds_read_b128 v[204:207], v174 offset:36864
	ds_read_b128 v[208:211], v174 offset:37888
	ds_read_b128 v[222:225], v174 offset:38912
	ds_read_b128 v[226:229], v174 offset:39936
	s_waitcnt vmcnt(2)
	s_barrier
	s_waitcnt lgkmcnt(0)
	s_setprio 1
	s_waitcnt lgkmcnt(7)
	v_mfma_f32_16x16x32_bf16 v[34:37], v[0:3], v[18:21], v[126:129]
	s_waitcnt lgkmcnt(6)
	v_mfma_f32_16x16x32_bf16 v[110:113], v[4:7], v[22:25], v[34:37]
	v_mfma_f32_16x16x32_bf16 v[34:37], v[196:199], v[18:21], v[122:125]
	v_mfma_f32_16x16x32_bf16 v[106:109], v[200:203], v[22:25], v[34:37]
	s_waitcnt lgkmcnt(5)
	v_mfma_f32_16x16x32_bf16 v[34:37], v[0:3], v[42:45], v[118:121]
	s_waitcnt lgkmcnt(4)
	v_mfma_f32_16x16x32_bf16 v[90:93], v[4:7], v[46:49], v[34:37]
	v_mfma_f32_16x16x32_bf16 v[34:37], v[196:199], v[42:45], v[114:117]
	v_mfma_f32_16x16x32_bf16 v[86:89], v[200:203], v[46:49], v[34:37]
	s_waitcnt lgkmcnt(3)
	v_mfma_f32_16x16x32_bf16 v[34:37], v[0:3], v[204:207], v[214:217]
	s_waitcnt lgkmcnt(2)
	v_mfma_f32_16x16x32_bf16 v[62:65], v[4:7], v[208:211], v[34:37]
	v_mfma_f32_16x16x32_bf16 v[34:37], v[196:199], v[204:207], v[218:221]
	v_mfma_f32_16x16x32_bf16 v[58:61], v[200:203], v[208:211], v[34:37]
	s_waitcnt lgkmcnt(1)
	v_mfma_f32_16x16x32_bf16 v[34:37], v[0:3], v[222:225], v[102:105]
	s_waitcnt lgkmcnt(0)
	v_mfma_f32_16x16x32_bf16 v[38:41], v[4:7], v[226:229], v[34:37]
	v_mfma_f32_16x16x32_bf16 v[34:37], v[196:199], v[222:225], v[98:101]
	v_mfma_f32_16x16x32_bf16 v[34:37], v[200:203], v[226:229], v[34:37]
	s_setprio 0
	s_nop 0
	v_add3_u32 v98, s91, v176, v149
	s_barrier
	ds_read_b128 v[214:217], v98
	ds_read_b128 v[218:221], v98 offset:1024
	ds_read_b128 v[246:249], v98 offset:2048
	ds_read_b128 v[250:253], v98 offset:3072
	s_waitcnt vmcnt(0)
	s_barrier
	s_waitcnt lgkmcnt(0)
	s_setprio 1
	s_waitcnt lgkmcnt(3)
	v_mfma_f32_16x16x32_bf16 v[94:97], v[214:217], v[18:21], v[94:97]
	s_waitcnt lgkmcnt(1)
	v_mfma_f32_16x16x32_bf16 v[18:21], v[246:249], v[18:21], v[166:169]
	s_waitcnt lgkmcnt(0)
	v_mfma_f32_16x16x32_bf16 v[122:125], v[250:253], v[22:25], v[18:21]
	v_mfma_f32_16x16x32_bf16 v[18:21], v[214:217], v[42:45], v[170:173]
	v_mfma_f32_16x16x32_bf16 v[118:121], v[218:221], v[46:49], v[18:21]
	v_mfma_f32_16x16x32_bf16 v[18:21], v[246:249], v[42:45], v[82:85]
	v_mfma_f32_16x16x32_bf16 v[114:117], v[250:253], v[46:49], v[18:21]
	v_mfma_f32_16x16x32_bf16 v[18:21], v[214:217], v[204:207], v[78:81]
	v_mfma_f32_16x16x32_bf16 v[102:105], v[218:221], v[208:211], v[18:21]
	v_mfma_f32_16x16x32_bf16 v[18:21], v[246:249], v[204:207], v[74:77]
	v_mfma_f32_16x16x32_bf16 v[126:129], v[218:221], v[22:25], v[94:97]
	v_mfma_f32_16x16x32_bf16 v[94:97], v[250:253], v[208:211], v[18:21]
	v_mfma_f32_16x16x32_bf16 v[18:21], v[214:217], v[222:225], v[70:73]
	v_mfma_f32_16x16x32_bf16 v[70:73], v[218:221], v[226:229], v[18:21]
	v_mfma_f32_16x16x32_bf16 v[18:21], v[246:249], v[222:225], v[66:69]
	v_mfma_f32_16x16x32_bf16 v[66:69], v[250:253], v[226:229], v[18:21]
	s_setprio 0
	s_barrier
	ds_read_b128 v[82:85], v190 offset:49152
	ds_read_b128 v[166:169], v190 offset:50176
	ds_read_b128 v[170:173], v174 offset:51200
	ds_read_b128 v[204:207], v174 offset:52224
	ds_read_b128 v[208:211], v174 offset:53248
	ds_read_b128 v[222:225], v174 offset:54272
	ds_read_b128 v[226:229], v174 offset:55296
	ds_read_b128 v[174:177], v174 offset:56320
	s_barrier
	s_waitcnt lgkmcnt(0)
	s_setprio 1
	s_waitcnt lgkmcnt(7)
	v_mfma_f32_16x16x32_bf16 v[18:21], v[0:3], v[82:85], v[230:233]
	s_waitcnt lgkmcnt(6)
	v_mfma_f32_16x16x32_bf16 v[78:81], v[4:7], v[166:169], v[18:21]
	v_mfma_f32_16x16x32_bf16 v[18:21], v[196:199], v[82:85], v[234:237]
	v_mfma_f32_16x16x32_bf16 v[74:77], v[200:203], v[166:169], v[18:21]
	s_waitcnt lgkmcnt(5)
	v_mfma_f32_16x16x32_bf16 v[18:21], v[0:3], v[170:173], v[54:57]
	s_waitcnt lgkmcnt(4)
	v_mfma_f32_16x16x32_bf16 v[46:49], v[4:7], v[204:207], v[18:21]
	v_mfma_f32_16x16x32_bf16 v[18:21], v[196:199], v[170:173], v[50:53]
	v_mfma_f32_16x16x32_bf16 v[42:45], v[200:203], v[204:207], v[18:21]
	s_waitcnt lgkmcnt(3)
	v_mfma_f32_16x16x32_bf16 v[18:21], v[0:3], v[208:211], v[238:241]
	s_waitcnt lgkmcnt(1)
	v_mfma_f32_16x16x32_bf16 v[0:3], v[0:3], v[226:229], v[150:153]
	v_mfma_f32_16x16x32_bf16 v[22:25], v[4:7], v[222:225], v[18:21]
	v_mfma_f32_16x16x32_bf16 v[18:21], v[196:199], v[208:211], v[242:245]
	s_waitcnt lgkmcnt(0)
	v_mfma_f32_16x16x32_bf16 v[4:7], v[4:7], v[174:177], v[0:3]
	v_mfma_f32_16x16x32_bf16 v[0:3], v[196:199], v[226:229], v[154:157]
	v_mfma_f32_16x16x32_bf16 v[18:21], v[200:203], v[222:225], v[18:21]
	v_mfma_f32_16x16x32_bf16 v[0:3], v[200:203], v[174:177], v[0:3]
	s_setprio 0
	s_setprio 1
	v_mfma_f32_16x16x32_bf16 v[26:29], v[246:249], v[82:85], v[26:29]
	v_mfma_f32_16x16x32_bf16 v[30:33], v[214:217], v[82:85], v[30:33]
	v_mfma_f32_16x16x32_bf16 v[82:85], v[250:253], v[166:169], v[26:29]
	v_mfma_f32_16x16x32_bf16 v[26:29], v[214:217], v[170:173], v[158:161]
	v_mfma_f32_16x16x32_bf16 v[54:57], v[218:221], v[204:207], v[26:29]
	v_mfma_f32_16x16x32_bf16 v[26:29], v[246:249], v[170:173], v[162:165]
	v_mfma_f32_16x16x32_bf16 v[8:11], v[246:249], v[208:211], v[8:11]
	v_mfma_f32_16x16x32_bf16 v[50:53], v[250:253], v[204:207], v[26:29]
	v_mfma_f32_16x16x32_bf16 v[12:15], v[214:217], v[208:211], v[12:15]
	v_mfma_f32_16x16x32_bf16 v[26:29], v[250:253], v[222:225], v[8:11]
	v_mfma_f32_16x16x32_bf16 v[8:11], v[214:217], v[226:229], v[178:181]
	v_mfma_f32_16x16x32_bf16 v[98:101], v[218:221], v[166:169], v[30:33]
	v_mfma_f32_16x16x32_bf16 v[30:33], v[218:221], v[222:225], v[12:15]
	v_mfma_f32_16x16x32_bf16 v[12:15], v[218:221], v[174:177], v[8:11]
	v_mfma_f32_16x16x32_bf16 v[8:11], v[246:249], v[226:229], v[182:185]
	v_mfma_f32_16x16x32_bf16 v[8:11], v[250:253], v[174:177], v[8:11]
	s_setprio 0
	s_movk_i32 s1, 0x100
	v_cmp_gt_u32_e32 vcc, s1, v144
	s_barrier
	s_and_saveexec_b64 s[6:7], vcc
	s_cbranch_execz .LBB0_529
	s_barrier

.LBB0_645:
	s_or_b64 exec, exec, s[12:13]
	s_add_i32 s29, s21, 0x18000
	s_or_b32 s12, s20, 0x80
	s_mov_b32 m0, s29
	s_add_i32 s30, s21, 0x1a000
	s_waitcnt vmcnt(4)
	s_barrier
	buffer_load_dwordx4 v134, s[52:55], s12 offen lds
	s_mov_b32 m0, s30
	s_add_i32 s31, s21, 0x8000
	buffer_load_dwordx4 v135, s[52:55], s12 offen lds
	s_or_b32 s12, s19, 0x80
	s_mov_b32 m0, s31
	s_add_i32 s34, s21, 0xa000
	buffer_load_dwordx4 v134, s[48:51], s12 offen lds
	s_mov_b32 m0, s34
	s_add_i32 s35, s21, 0x1c000
	buffer_load_dwordx4 v135, s[48:51], s12 offen lds
	s_or_b32 s12, s20, 0x80080
	s_mov_b32 m0, s35
	s_add_i32 s36, s21, 0x1e000
	buffer_load_dwordx4 v134, s[52:55], s12 offen lds
	s_mov_b32 m0, s36
	v_mov_b32_e32 v0, 0
	buffer_load_dwordx4 v135, s[52:55], s12 offen lds
	s_waitcnt vmcnt(6)
	s_add_i32 s13, s21, 0xc000
	s_add_i32 s12, s21, 0xe000
	s_mov_b32 s37, -2
	s_mov_b32 s38, 0
	v_mov_b32_e32 v1, v0
	v_mov_b32_e32 v2, v0
	v_mov_b32_e32 v3, v0
	v_mov_b32_e32 v4, v0
	v_mov_b32_e32 v5, v0
	v_mov_b32_e32 v6, v0
	v_mov_b32_e32 v7, v0
	v_mov_b32_e32 v8, v0
	v_mov_b32_e32 v9, v0
	v_mov_b32_e32 v10, v0
	v_mov_b32_e32 v11, v0
	v_mov_b32_e32 v12, v0
	v_mov_b32_e32 v13, v0
	v_mov_b32_e32 v14, v0
	v_mov_b32_e32 v15, v0
	v_mov_b32_e32 v18, v0
	v_mov_b32_e32 v19, v0
	v_mov_b32_e32 v20, v0
	v_mov_b32_e32 v21, v0
	v_mov_b32_e32 v22, v0
	v_mov_b32_e32 v23, v0
	v_mov_b32_e32 v24, v0
	v_mov_b32_e32 v25, v0
	v_mov_b32_e32 v26, v0
	v_mov_b32_e32 v27, v0
	v_mov_b32_e32 v28, v0
	v_mov_b32_e32 v29, v0
	v_mov_b32_e32 v30, v0
	v_mov_b32_e32 v31, v0
	v_mov_b32_e32 v32, v0
	v_mov_b32_e32 v33, v0
	v_mov_b32_e32 v34, v0
	v_mov_b32_e32 v35, v0
	v_mov_b32_e32 v36, v0
	v_mov_b32_e32 v37, v0
	v_mov_b32_e32 v38, v0
	v_mov_b32_e32 v39, v0
	v_mov_b32_e32 v40, v0
	v_mov_b32_e32 v41, v0
	v_mov_b32_e32 v42, v0
	v_mov_b32_e32 v43, v0
	v_mov_b32_e32 v44, v0
	v_mov_b32_e32 v45, v0
	v_mov_b32_e32 v46, v0
	v_mov_b32_e32 v47, v0
	v_mov_b32_e32 v48, v0
	v_mov_b32_e32 v49, v0
	v_mov_b32_e32 v50, v0
	v_mov_b32_e32 v51, v0
	v_mov_b32_e32 v52, v0
	v_mov_b32_e32 v53, v0
	v_mov_b32_e32 v54, v0
	v_mov_b32_e32 v55, v0
	v_mov_b32_e32 v56, v0
	v_mov_b32_e32 v57, v0
	v_mov_b32_e32 v58, v0
	v_mov_b32_e32 v59, v0
	v_mov_b32_e32 v60, v0
	v_mov_b32_e32 v61, v0
	v_mov_b32_e32 v62, v0
	v_mov_b32_e32 v63, v0
	v_mov_b32_e32 v64, v0
	v_mov_b32_e32 v65, v0
	v_mov_b32_e32 v66, v0
	v_mov_b32_e32 v67, v0
	v_mov_b32_e32 v68, v0
	v_mov_b32_e32 v69, v0
	v_mov_b32_e32 v70, v0
	v_mov_b32_e32 v71, v0
	v_mov_b32_e32 v72, v0
	v_mov_b32_e32 v73, v0
	v_mov_b32_e32 v74, v0
	v_mov_b32_e32 v75, v0
	v_mov_b32_e32 v76, v0
	v_mov_b32_e32 v77, v0
	v_mov_b32_e32 v78, v0
	v_mov_b32_e32 v79, v0
	v_mov_b32_e32 v80, v0
	v_mov_b32_e32 v81, v0
	v_mov_b32_e32 v82, v0
	v_mov_b32_e32 v83, v0
	v_mov_b32_e32 v84, v0
	v_mov_b32_e32 v85, v0
	v_mov_b32_e32 v86, v0
	v_mov_b32_e32 v87, v0
	v_mov_b32_e32 v88, v0
	v_mov_b32_e32 v89, v0
	v_mov_b32_e32 v90, v0
	v_mov_b32_e32 v91, v0
	v_mov_b32_e32 v92, v0
	v_mov_b32_e32 v93, v0
	v_mov_b32_e32 v94, v0
	v_mov_b32_e32 v95, v0
	v_mov_b32_e32 v96, v0
	v_mov_b32_e32 v97, v0
	v_mov_b32_e32 v98, v0
	v_mov_b32_e32 v99, v0
	v_mov_b32_e32 v100, v0
	v_mov_b32_e32 v101, v0
	v_mov_b32_e32 v102, v0
	v_mov_b32_e32 v103, v0
	v_mov_b32_e32 v104, v0
	v_mov_b32_e32 v105, v0
	v_mov_b32_e32 v106, v0
	v_mov_b32_e32 v107, v0
	v_mov_b32_e32 v108, v0
	v_mov_b32_e32 v109, v0
	v_mov_b32_e32 v110, v0
	v_mov_b32_e32 v111, v0
	v_mov_b32_e32 v112, v0
	v_mov_b32_e32 v113, v0
	v_mov_b32_e32 v114, v0
	v_mov_b32_e32 v115, v0
	v_mov_b32_e32 v116, v0
	v_mov_b32_e32 v117, v0
	v_mov_b32_e32 v118, v0
	v_mov_b32_e32 v119, v0
	v_mov_b32_e32 v120, v0
	v_mov_b32_e32 v121, v0
	v_mov_b32_e32 v122, v0
	v_mov_b32_e32 v123, v0
	v_mov_b32_e32 v124, v0
	v_mov_b32_e32 v125, v0
	v_mov_b32_e32 v126, v0
	v_mov_b32_e32 v127, v0
	v_mov_b32_e32 v128, v0
	v_mov_b32_e32 v129, v0
	s_barrier
	s_nop 0
.LBB0_646:
	ds_read_b128 v[144:147], v136
	ds_read_b128 v[148:151], v136 offset:1024
	ds_read_b128 v[152:155], v136 offset:2048
	ds_read_b128 v[156:159], v136 offset:3072
	s_add_i32 s39, s19, s38
	s_add_i32 s61, s39, 0x80080
	s_mov_b32 m0, s13
	ds_read_b128 v[160:163], v137
	ds_read_b128 v[164:167], v137 offset:1024
	ds_read_b128 v[168:171], v138
	ds_read_b128 v[172:175], v138 offset:1024
	ds_read_b128 v[176:179], v139
	ds_read_b128 v[180:183], v139 offset:1024
	ds_read_b128 v[196:199], v140
	ds_read_b128 v[200:203], v140 offset:1024
	buffer_load_dwordx4 v134, s[48:51], s61 offen lds
	s_mov_b32 m0, s12
	s_nop 0
	buffer_load_dwordx4 v135, s[48:51], s61 offen lds
	s_waitcnt lgkmcnt(8)
	s_barrier
	s_waitcnt lgkmcnt(0)
	s_setprio 1
	s_waitcnt lgkmcnt(0)
	v_mfma_f32_16x16x32_bf16 v[126:129], v[144:147], v[160:163], v[126:129]
	v_mfma_f32_16x16x32_bf16 v[122:125], v[152:155], v[160:163], v[122:125]
	v_mfma_f32_16x16x32_bf16 v[118:121], v[144:147], v[168:171], v[118:121]
	v_mfma_f32_16x16x32_bf16 v[114:117], v[152:155], v[168:171], v[114:117]
	v_mfma_f32_16x16x32_bf16 v[110:113], v[144:147], v[176:179], v[110:113]
	v_mfma_f32_16x16x32_bf16 v[106:109], v[152:155], v[176:179], v[106:109]
	v_mfma_f32_16x16x32_bf16 v[102:105], v[144:147], v[196:199], v[102:105]
	v_mfma_f32_16x16x32_bf16 v[98:101], v[152:155], v[196:199], v[98:101]
	v_mfma_f32_16x16x32_bf16 v[126:129], v[148:151], v[164:167], v[126:129]
	v_mfma_f32_16x16x32_bf16 v[122:125], v[156:159], v[164:167], v[122:125]
	v_mfma_f32_16x16x32_bf16 v[118:121], v[148:151], v[172:175], v[118:121]
	v_mfma_f32_16x16x32_bf16 v[114:117], v[156:159], v[172:175], v[114:117]
	v_mfma_f32_16x16x32_bf16 v[110:113], v[148:151], v[180:183], v[110:113]
	v_mfma_f32_16x16x32_bf16 v[106:109], v[156:159], v[180:183], v[106:109]
	v_mfma_f32_16x16x32_bf16 v[102:105], v[148:151], v[200:203], v[102:105]
	v_mfma_f32_16x16x32_bf16 v[98:101], v[156:159], v[200:203], v[98:101]
	s_setprio 0
	s_barrier
	s_add_i32 s61, s20, s38
	s_add_i32 s62, s61, 0x100
	s_mov_b32 m0, s22
	ds_read_b128 v[204:207], v141
	ds_read_b128 v[208:211], v141 offset:1024
	ds_read_b128 v[214:217], v141 offset:2048
	ds_read_b128 v[218:221], v141 offset:3072
	buffer_load_dwordx4 v134, s[52:55], s62 offen lds
	s_mov_b32 m0, s23
	s_nop 0
	buffer_load_dwordx4 v135, s[52:55], s62 offen lds
	s_barrier
	s_waitcnt lgkmcnt(0)
	s_setprio 1
	s_waitcnt lgkmcnt(0)
	v_mfma_f32_16x16x32_bf16 v[94:97], v[204:207], v[160:163], v[94:97]
	v_mfma_f32_16x16x32_bf16 v[90:93], v[214:217], v[160:163], v[90:93]
	v_mfma_f32_16x16x32_bf16 v[86:89], v[204:207], v[168:171], v[86:89]
	v_mfma_f32_16x16x32_bf16 v[82:85], v[214:217], v[168:171], v[82:85]
	v_mfma_f32_16x16x32_bf16 v[78:81], v[204:207], v[176:179], v[78:81]
	v_mfma_f32_16x16x32_bf16 v[74:77], v[214:217], v[176:179], v[74:77]
	v_mfma_f32_16x16x32_bf16 v[70:73], v[204:207], v[196:199], v[70:73]
	v_mfma_f32_16x16x32_bf16 v[66:69], v[214:217], v[196:199], v[66:69]
	v_mfma_f32_16x16x32_bf16 v[94:97], v[208:211], v[164:167], v[94:97]
	v_mfma_f32_16x16x32_bf16 v[90:93], v[218:221], v[164:167], v[90:93]
	v_mfma_f32_16x16x32_bf16 v[86:89], v[208:211], v[172:175], v[86:89]
	v_mfma_f32_16x16x32_bf16 v[82:85], v[218:221], v[172:175], v[82:85]
	v_mfma_f32_16x16x32_bf16 v[78:81], v[208:211], v[180:183], v[78:81]
	v_mfma_f32_16x16x32_bf16 v[74:77], v[218:221], v[180:183], v[74:77]
	v_mfma_f32_16x16x32_bf16 v[70:73], v[208:211], v[200:203], v[70:73]
	v_mfma_f32_16x16x32_bf16 v[66:69], v[218:221], v[200:203], v[66:69]
	s_setprio 0
	s_add_i32 s62, s39, 0x100
	s_mov_b32 m0, s21
	s_barrier
	ds_read_b128 v[160:163], v137 offset:16384
	ds_read_b128 v[164:167], v137 offset:17408
	ds_read_b128 v[168:171], v138 offset:16384
	ds_read_b128 v[172:175], v138 offset:17408
	ds_read_b128 v[176:179], v139 offset:16384
	ds_read_b128 v[180:183], v139 offset:17408
	ds_read_b128 v[196:199], v140 offset:16384
	ds_read_b128 v[200:203], v140 offset:17408
	buffer_load_dwordx4 v134, s[48:51], s62 offen lds
	s_mov_b32 m0, s24
	s_nop 0
	buffer_load_dwordx4 v135, s[48:51], s62 offen lds
	s_barrier
	s_waitcnt lgkmcnt(0)
	s_setprio 1
	s_waitcnt lgkmcnt(0)
	v_mfma_f32_16x16x32_bf16 v[62:65], v[144:147], v[160:163], v[62:65]
	v_mfma_f32_16x16x32_bf16 v[58:61], v[152:155], v[160:163], v[58:61]
	v_mfma_f32_16x16x32_bf16 v[54:57], v[144:147], v[168:171], v[54:57]
	v_mfma_f32_16x16x32_bf16 v[50:53], v[152:155], v[168:171], v[50:53]
	v_mfma_f32_16x16x32_bf16 v[46:49], v[144:147], v[176:179], v[46:49]
	v_mfma_f32_16x16x32_bf16 v[42:45], v[152:155], v[176:179], v[42:45]
	v_mfma_f32_16x16x32_bf16 v[38:41], v[144:147], v[196:199], v[38:41]
	v_mfma_f32_16x16x32_bf16 v[34:37], v[152:155], v[196:199], v[34:37]
	v_mfma_f32_16x16x32_bf16 v[62:65], v[148:151], v[164:167], v[62:65]
	v_mfma_f32_16x16x32_bf16 v[58:61], v[156:159], v[164:167], v[58:61]
	v_mfma_f32_16x16x32_bf16 v[54:57], v[148:151], v[172:175], v[54:57]
	v_mfma_f32_16x16x32_bf16 v[50:53], v[156:159], v[172:175], v[50:53]
	v_mfma_f32_16x16x32_bf16 v[46:49], v[148:151], v[180:183], v[46:49]
	v_mfma_f32_16x16x32_bf16 v[42:45], v[156:159], v[180:183], v[42:45]
	v_mfma_f32_16x16x32_bf16 v[38:41], v[148:151], v[200:203], v[38:41]
	v_mfma_f32_16x16x32_bf16 v[34:37], v[156:159], v[200:203], v[34:37]
	s_setprio 0
	s_barrier
	s_add_i32 s62, s61, 0x80100
	s_mov_b32 m0, s25
	s_nop 0
	buffer_load_dwordx4 v134, s[52:55], s62 offen lds
	s_mov_b32 m0, s26
	s_nop 0
	buffer_load_dwordx4 v135, s[52:55], s62 offen lds
	s_waitcnt vmcnt(6)
	s_barrier
	s_setprio 1
	v_mfma_f32_16x16x32_bf16 v[30:33], v[204:207], v[160:163], v[30:33]
	v_mfma_f32_16x16x32_bf16 v[26:29], v[214:217], v[160:163], v[26:29]
	v_mfma_f32_16x16x32_bf16 v[22:25], v[204:207], v[168:171], v[22:25]
	v_mfma_f32_16x16x32_bf16 v[18:21], v[214:217], v[168:171], v[18:21]
	v_mfma_f32_16x16x32_bf16 v[12:15], v[204:207], v[176:179], v[12:15]
	v_mfma_f32_16x16x32_bf16 v[8:11], v[214:217], v[176:179], v[8:11]
	v_mfma_f32_16x16x32_bf16 v[4:7], v[204:207], v[196:199], v[4:7]
	v_mfma_f32_16x16x32_bf16 v[0:3], v[214:217], v[196:199], v[0:3]
	v_mfma_f32_16x16x32_bf16 v[30:33], v[208:211], v[164:167], v[30:33]
	v_mfma_f32_16x16x32_bf16 v[26:29], v[218:221], v[164:167], v[26:29]
	v_mfma_f32_16x16x32_bf16 v[22:25], v[208:211], v[172:175], v[22:25]
	v_mfma_f32_16x16x32_bf16 v[18:21], v[218:221], v[172:175], v[18:21]
	v_mfma_f32_16x16x32_bf16 v[12:15], v[208:211], v[180:183], v[12:15]
	v_mfma_f32_16x16x32_bf16 v[8:11], v[218:221], v[180:183], v[8:11]
	v_mfma_f32_16x16x32_bf16 v[4:7], v[208:211], v[200:203], v[4:7]
	v_mfma_f32_16x16x32_bf16 v[0:3], v[218:221], v[200:203], v[0:3]
	s_setprio 0
	s_barrier
	ds_read_b128 v[144:147], v142
	ds_read_b128 v[148:151], v142 offset:1024
	ds_read_b128 v[152:155], v142 offset:2048
	ds_read_b128 v[156:159], v142 offset:3072
	s_add_i32 s62, s39, 0x80100
	s_mov_b32 m0, s27
	ds_read_b128 v[160:163], v137 offset:32768
	ds_read_b128 v[164:167], v137 offset:33792
	ds_read_b128 v[168:171], v138 offset:32768
	ds_read_b128 v[172:175], v138 offset:33792
	ds_read_b128 v[176:179], v139 offset:32768
	ds_read_b128 v[180:183], v139 offset:33792
	ds_read_b128 v[196:199], v140 offset:32768
	ds_read_b128 v[200:203], v140 offset:33792
	buffer_load_dwordx4 v134, s[48:51], s62 offen lds
	s_mov_b32 m0, s28
	s_nop 0
	buffer_load_dwordx4 v135, s[48:51], s62 offen lds
	s_waitcnt lgkmcnt(8)
	s_barrier
	s_waitcnt lgkmcnt(0)
	s_setprio 1
	s_waitcnt lgkmcnt(0)
	v_mfma_f32_16x16x32_bf16 v[126:129], v[144:147], v[160:163], v[126:129]
	v_mfma_f32_16x16x32_bf16 v[122:125], v[152:155], v[160:163], v[122:125]
	v_mfma_f32_16x16x32_bf16 v[118:121], v[144:147], v[168:171], v[118:121]
	v_mfma_f32_16x16x32_bf16 v[114:117], v[152:155], v[168:171], v[114:117]
	v_mfma_f32_16x16x32_bf16 v[110:113], v[144:147], v[176:179], v[110:113]
	v_mfma_f32_16x16x32_bf16 v[106:109], v[152:155], v[176:179], v[106:109]
	v_mfma_f32_16x16x32_bf16 v[102:105], v[144:147], v[196:199], v[102:105]
	v_mfma_f32_16x16x32_bf16 v[98:101], v[152:155], v[196:199], v[98:101]
	v_mfma_f32_16x16x32_bf16 v[126:129], v[148:151], v[164:167], v[126:129]
	v_mfma_f32_16x16x32_bf16 v[122:125], v[156:159], v[164:167], v[122:125]
	v_mfma_f32_16x16x32_bf16 v[118:121], v[148:151], v[172:175], v[118:121]
	v_mfma_f32_16x16x32_bf16 v[114:117], v[156:159], v[172:175], v[114:117]
	v_mfma_f32_16x16x32_bf16 v[110:113], v[148:151], v[180:183], v[110:113]
	v_mfma_f32_16x16x32_bf16 v[106:109], v[156:159], v[180:183], v[106:109]
	v_mfma_f32_16x16x32_bf16 v[102:105], v[148:151], v[200:203], v[102:105]
	v_mfma_f32_16x16x32_bf16 v[98:101], v[156:159], v[200:203], v[98:101]
	s_setprio 0
	s_barrier
	s_add_i32 s62, s61, 0x180
	s_mov_b32 m0, s29
	ds_read_b128 v[204:207], v143
	ds_read_b128 v[208:211], v143 offset:1024
	ds_read_b128 v[214:217], v143 offset:2048
	ds_read_b128 v[218:221], v143 offset:3072
	buffer_load_dwordx4 v134, s[52:55], s62 offen lds
	s_mov_b32 m0, s30
	s_nop 0
	buffer_load_dwordx4 v135, s[52:55], s62 offen lds
	s_barrier
	s_waitcnt lgkmcnt(0)
	s_setprio 1
	s_waitcnt lgkmcnt(0)
	v_mfma_f32_16x16x32_bf16 v[94:97], v[204:207], v[160:163], v[94:97]
	v_mfma_f32_16x16x32_bf16 v[90:93], v[214:217], v[160:163], v[90:93]
	v_mfma_f32_16x16x32_bf16 v[86:89], v[204:207], v[168:171], v[86:89]
	v_mfma_f32_16x16x32_bf16 v[82:85], v[214:217], v[168:171], v[82:85]
	v_mfma_f32_16x16x32_bf16 v[78:81], v[204:207], v[176:179], v[78:81]
	v_mfma_f32_16x16x32_bf16 v[74:77], v[214:217], v[176:179], v[74:77]
	v_mfma_f32_16x16x32_bf16 v[70:73], v[204:207], v[196:199], v[70:73]
	v_mfma_f32_16x16x32_bf16 v[66:69], v[214:217], v[196:199], v[66:69]
	v_mfma_f32_16x16x32_bf16 v[94:97], v[208:211], v[164:167], v[94:97]
	v_mfma_f32_16x16x32_bf16 v[90:93], v[218:221], v[164:167], v[90:93]
	v_mfma_f32_16x16x32_bf16 v[86:89], v[208:211], v[172:175], v[86:89]
	v_mfma_f32_16x16x32_bf16 v[82:85], v[218:221], v[172:175], v[82:85]
	v_mfma_f32_16x16x32_bf16 v[78:81], v[208:211], v[180:183], v[78:81]
	v_mfma_f32_16x16x32_bf16 v[74:77], v[218:221], v[180:183], v[74:77]
	v_mfma_f32_16x16x32_bf16 v[70:73], v[208:211], v[200:203], v[70:73]
	v_mfma_f32_16x16x32_bf16 v[66:69], v[218:221], v[200:203], v[66:69]
	s_setprio 0
	s_addk_i32 s39, 0x180
	s_mov_b32 m0, s31
	s_barrier
	ds_read_b128 v[160:163], v137 offset:49152
	ds_read_b128 v[164:167], v137 offset:50176
	ds_read_b128 v[168:171], v138 offset:49152
	ds_read_b128 v[172:175], v138 offset:50176
	ds_read_b128 v[176:179], v139 offset:49152
	ds_read_b128 v[180:183], v139 offset:50176
	ds_read_b128 v[196:199], v140 offset:49152
	ds_read_b128 v[200:203], v140 offset:50176
	buffer_load_dwordx4 v134, s[48:51], s39 offen lds
	s_mov_b32 m0, s34
	s_nop 0
	buffer_load_dwordx4 v135, s[48:51], s39 offen lds
	s_barrier
	s_waitcnt lgkmcnt(0)
	s_setprio 1
	s_waitcnt lgkmcnt(0)
	v_mfma_f32_16x16x32_bf16 v[62:65], v[144:147], v[160:163], v[62:65]
	v_mfma_f32_16x16x32_bf16 v[58:61], v[152:155], v[160:163], v[58:61]
	v_mfma_f32_16x16x32_bf16 v[54:57], v[144:147], v[168:171], v[54:57]
	v_mfma_f32_16x16x32_bf16 v[50:53], v[152:155], v[168:171], v[50:53]
	v_mfma_f32_16x16x32_bf16 v[46:49], v[144:147], v[176:179], v[46:49]
	v_mfma_f32_16x16x32_bf16 v[42:45], v[152:155], v[176:179], v[42:45]
	v_mfma_f32_16x16x32_bf16 v[38:41], v[144:147], v[196:199], v[38:41]
	v_mfma_f32_16x16x32_bf16 v[34:37], v[152:155], v[196:199], v[34:37]
	v_mfma_f32_16x16x32_bf16 v[62:65], v[148:151], v[164:167], v[62:65]
	v_mfma_f32_16x16x32_bf16 v[58:61], v[156:159], v[164:167], v[58:61]
	v_mfma_f32_16x16x32_bf16 v[54:57], v[148:151], v[172:175], v[54:57]
	v_mfma_f32_16x16x32_bf16 v[50:53], v[156:159], v[172:175], v[50:53]
	v_mfma_f32_16x16x32_bf16 v[46:49], v[148:151], v[180:183], v[46:49]
	v_mfma_f32_16x16x32_bf16 v[42:45], v[156:159], v[180:183], v[42:45]
	v_mfma_f32_16x16x32_bf16 v[38:41], v[148:151], v[200:203], v[38:41]
	v_mfma_f32_16x16x32_bf16 v[34:37], v[156:159], v[200:203], v[34:37]
	s_setprio 0
	s_barrier
	s_add_i32 s61, s61, 0x80180
	s_mov_b32 m0, s35
	s_nop 0
	buffer_load_dwordx4 v134, s[52:55], s61 offen lds
	s_mov_b32 m0, s36
	s_nop 0
	buffer_load_dwordx4 v135, s[52:55], s61 offen lds
	s_waitcnt vmcnt(6)
	s_barrier
	s_setprio 1
	v_mfma_f32_16x16x32_bf16 v[30:33], v[204:207], v[160:163], v[30:33]
	v_mfma_f32_16x16x32_bf16 v[26:29], v[214:217], v[160:163], v[26:29]
	v_mfma_f32_16x16x32_bf16 v[22:25], v[204:207], v[168:171], v[22:25]
	v_mfma_f32_16x16x32_bf16 v[18:21], v[214:217], v[168:171], v[18:21]
	v_mfma_f32_16x16x32_bf16 v[12:15], v[204:207], v[176:179], v[12:15]
	v_mfma_f32_16x16x32_bf16 v[8:11], v[214:217], v[176:179], v[8:11]
	v_mfma_f32_16x16x32_bf16 v[4:7], v[204:207], v[196:199], v[4:7]
	v_mfma_f32_16x16x32_bf16 v[0:3], v[214:217], v[196:199], v[0:3]
	v_mfma_f32_16x16x32_bf16 v[30:33], v[208:211], v[164:167], v[30:33]
	v_mfma_f32_16x16x32_bf16 v[26:29], v[218:221], v[164:167], v[26:29]
	v_mfma_f32_16x16x32_bf16 v[22:25], v[208:211], v[172:175], v[22:25]
	v_mfma_f32_16x16x32_bf16 v[18:21], v[218:221], v[172:175], v[18:21]
	v_mfma_f32_16x16x32_bf16 v[12:15], v[208:211], v[180:183], v[12:15]
	v_mfma_f32_16x16x32_bf16 v[8:11], v[218:221], v[180:183], v[8:11]
	v_mfma_f32_16x16x32_bf16 v[4:7], v[208:211], v[200:203], v[4:7]
	v_mfma_f32_16x16x32_bf16 v[0:3], v[218:221], v[200:203], v[0:3]
	s_setprio 0
	s_add_i32 s37, s37, 2
	s_addk_i32 s38, 0x100
	s_cmp_lt_u32 s37, 28
	s_barrier
	s_cbranch_scc1 .LBB0_646
	s_nop 0
	v_mov_b32_e32 v144, v130
	s_or_b32 s19, s19, 0x80f80
	v_and_b32_e32 v147, 15, v144
	v_bfe_u32 v146, v144, 4, 2
	v_lshlrev_b32_e32 v150, 2, v144
	v_bfe_u32 v145, v144, 6, 2
	v_lshlrev_b32_e32 v174, 4, v146
	v_lshlrev_b32_e32 v148, 6, v147
	v_and_b32_e32 v175, 32, v150
	v_lshlrev_b32_e32 v149, 12, v145
	v_bitop3_b32 v190, v174, v175, v148 bitop3:0x36
	v_add3_u32 v148, s78, v190, v149
	ds_read_b128 v[150:153], v148
	ds_read_b128 v[154:157], v148 offset:1024
	ds_read_b128 v[158:161], v148 offset:2048
	ds_read_b128 v[162:165], v148 offset:3072
	v_ashrrev_i32_e32 v148, 2, v144
	v_lshlrev_b32_e32 v177, 6, v144
	v_and_b32_e32 v148, 0xffffffc0, v148
	v_and_b32_e32 v177, 0x3c0, v177
	v_lshlrev_b32_e32 v176, 7, v148
	v_bitop3_b32 v174, v177, v175, v174 bitop3:0x36
	s_waitcnt vmcnt(0)
	v_add3_u32 v250, 0, v190, v176
	v_add3_u32 v251, 0, v174, v176
	s_mov_b32 m0, s13
	ds_read_b128 v[166:169], v250
	ds_read_b128 v[170:173], v250 offset:1024
	ds_read_b128 v[174:177], v251 offset:2048
	ds_read_b128 v[178:181], v251 offset:3072
	ds_read_b128 v[182:185], v251 offset:4096
	ds_read_b128 v[196:199], v251 offset:5120
	ds_read_b128 v[200:203], v251 offset:6144
	ds_read_b128 v[204:207], v251 offset:7168
	buffer_load_dwordx4 v134, s[48:51], s19 offen lds
	s_mov_b32 m0, s12
	s_nop 0
	buffer_load_dwordx4 v135, s[48:51], s19 offen lds
	s_barrier
	s_waitcnt lgkmcnt(0)
	s_setprio 1
	s_waitcnt lgkmcnt(0)
	v_mfma_f32_16x16x32_bf16 v[126:129], v[150:153], v[166:169], v[126:129]
	v_mfma_f32_16x16x32_bf16 v[122:125], v[158:161], v[166:169], v[122:125]
	v_mfma_f32_16x16x32_bf16 v[118:121], v[150:153], v[174:177], v[118:121]
	v_mfma_f32_16x16x32_bf16 v[114:117], v[158:161], v[174:177], v[114:117]
	v_mfma_f32_16x16x32_bf16 v[102:105], v[150:153], v[200:203], v[102:105]
	v_mfma_f32_16x16x32_bf16 v[98:101], v[158:161], v[200:203], v[98:101]
	v_mfma_f32_16x16x32_bf16 v[126:129], v[154:157], v[170:173], v[126:129]
	v_mfma_f32_16x16x32_bf16 v[122:125], v[162:165], v[170:173], v[122:125]
	v_mfma_f32_16x16x32_bf16 v[118:121], v[154:157], v[178:181], v[118:121]
	v_mfma_f32_16x16x32_bf16 v[114:117], v[162:165], v[178:181], v[114:117]
	v_mfma_f32_16x16x32_bf16 v[110:113], v[150:153], v[182:185], v[110:113]
	v_mfma_f32_16x16x32_bf16 v[106:109], v[158:161], v[182:185], v[106:109]
	v_mfma_f32_16x16x32_bf16 v[102:105], v[154:157], v[204:207], v[102:105]
	v_mfma_f32_16x16x32_bf16 v[98:101], v[162:165], v[204:207], v[98:101]
	v_mfma_f32_16x16x32_bf16 v[208:211], v[154:157], v[196:199], v[110:113]
	v_mfma_f32_16x16x32_bf16 v[214:217], v[162:165], v[196:199], v[106:109]
	s_setprio 0
	v_add3_u32 v222, s77, v190, v149
	s_barrier
	s_nop 0
	ds_read_b128 v[106:109], v222
	ds_read_b128 v[110:113], v222 offset:1024
	ds_read_b128 v[218:221], v222 offset:2048
	ds_read_b128 v[222:225], v222 offset:3072
	s_barrier
	s_waitcnt lgkmcnt(0)
	s_setprio 1
	s_waitcnt lgkmcnt(0)
	v_mfma_f32_16x16x32_bf16 v[94:97], v[106:109], v[166:169], v[94:97]
	v_mfma_f32_16x16x32_bf16 v[82:85], v[218:221], v[174:177], v[82:85]
	v_mfma_f32_16x16x32_bf16 v[78:81], v[106:109], v[182:185], v[78:81]
	v_mfma_f32_16x16x32_bf16 v[74:77], v[218:221], v[182:185], v[74:77]
	v_mfma_f32_16x16x32_bf16 v[70:73], v[106:109], v[200:203], v[70:73]
	v_mfma_f32_16x16x32_bf16 v[66:69], v[218:221], v[200:203], v[66:69]
	v_mfma_f32_16x16x32_bf16 v[94:97], v[110:113], v[170:173], v[94:97]
	v_mfma_f32_16x16x32_bf16 v[90:93], v[218:221], v[166:169], v[90:93]
	v_mfma_f32_16x16x32_bf16 v[86:89], v[106:109], v[174:177], v[86:89]
	v_mfma_f32_16x16x32_bf16 v[82:85], v[222:225], v[178:181], v[82:85]
	v_mfma_f32_16x16x32_bf16 v[78:81], v[110:113], v[196:199], v[78:81]
	v_mfma_f32_16x16x32_bf16 v[74:77], v[222:225], v[196:199], v[74:77]
	v_mfma_f32_16x16x32_bf16 v[70:73], v[110:113], v[204:207], v[70:73]
	v_mfma_f32_16x16x32_bf16 v[66:69], v[222:225], v[204:207], v[66:69]
	v_mfma_f32_16x16x32_bf16 v[166:169], v[222:225], v[170:173], v[90:93]
	v_mfma_f32_16x16x32_bf16 v[170:173], v[110:113], v[178:181], v[86:89]
	s_setprio 0
	s_barrier
	s_nop 0
	ds_read_b128 v[86:89], v250 offset:16384
	ds_read_b128 v[90:93], v250 offset:17408
	ds_read_b128 v[174:177], v251 offset:18432
	ds_read_b128 v[178:181], v251 offset:19456
	ds_read_b128 v[182:185], v251 offset:20480
	ds_read_b128 v[196:199], v251 offset:21504
	ds_read_b128 v[200:203], v251 offset:22528
	ds_read_b128 v[204:207], v251 offset:23552
	s_waitcnt vmcnt(4)
	s_barrier
	s_waitcnt lgkmcnt(0)
	s_setprio 1
	s_waitcnt lgkmcnt(0)
	v_mfma_f32_16x16x32_bf16 v[54:57], v[150:153], v[174:177], v[54:57]
	v_mfma_f32_16x16x32_bf16 v[50:53], v[158:161], v[174:177], v[50:53]
	v_mfma_f32_16x16x32_bf16 v[62:65], v[150:153], v[86:89], v[62:65]
	v_mfma_f32_16x16x32_bf16 v[58:61], v[158:161], v[86:89], v[58:61]
	v_mfma_f32_16x16x32_bf16 v[54:57], v[154:157], v[178:181], v[54:57]
	v_mfma_f32_16x16x32_bf16 v[50:53], v[162:165], v[178:181], v[50:53]
	v_mfma_f32_16x16x32_bf16 v[46:49], v[150:153], v[182:185], v[46:49]
	v_mfma_f32_16x16x32_bf16 v[42:45], v[158:161], v[182:185], v[42:45]
	v_mfma_f32_16x16x32_bf16 v[38:41], v[150:153], v[200:203], v[38:41]
	v_mfma_f32_16x16x32_bf16 v[34:37], v[158:161], v[200:203], v[34:37]
	v_mfma_f32_16x16x32_bf16 v[226:229], v[154:157], v[90:93], v[62:65]
	v_mfma_f32_16x16x32_bf16 v[230:233], v[162:165], v[90:93], v[58:61]
	v_mfma_f32_16x16x32_bf16 v[234:237], v[154:157], v[196:199], v[46:49]
	v_mfma_f32_16x16x32_bf16 v[238:241], v[162:165], v[196:199], v[42:45]
	v_mfma_f32_16x16x32_bf16 v[150:153], v[154:157], v[204:207], v[38:41]
	v_mfma_f32_16x16x32_bf16 v[154:157], v[162:165], v[204:207], v[34:37]
	s_setprio 0
	s_setprio 1
	v_mfma_f32_16x16x32_bf16 v[30:33], v[106:109], v[86:89], v[30:33]
	v_mfma_f32_16x16x32_bf16 v[26:29], v[218:221], v[86:89], v[26:29]
	v_mfma_f32_16x16x32_bf16 v[12:15], v[106:109], v[182:185], v[12:15]
	v_mfma_f32_16x16x32_bf16 v[8:11], v[218:221], v[182:185], v[8:11]
	v_mfma_f32_16x16x32_bf16 v[30:33], v[110:113], v[90:93], v[30:33]
	v_mfma_f32_16x16x32_bf16 v[26:29], v[222:225], v[90:93], v[26:29]
	v_mfma_f32_16x16x32_bf16 v[22:25], v[106:109], v[174:177], v[22:25]
	v_mfma_f32_16x16x32_bf16 v[18:21], v[218:221], v[174:177], v[18:21]
	v_mfma_f32_16x16x32_bf16 v[12:15], v[110:113], v[196:199], v[12:15]
	v_mfma_f32_16x16x32_bf16 v[8:11], v[222:225], v[196:199], v[8:11]
	v_mfma_f32_16x16x32_bf16 v[4:7], v[106:109], v[200:203], v[4:7]
	v_mfma_f32_16x16x32_bf16 v[0:3], v[218:221], v[200:203], v[0:3]
	v_mfma_f32_16x16x32_bf16 v[158:161], v[110:113], v[178:181], v[22:25]
	v_mfma_f32_16x16x32_bf16 v[162:165], v[222:225], v[178:181], v[18:21]
	v_mfma_f32_16x16x32_bf16 v[174:177], v[110:113], v[204:207], v[4:7]
	v_mfma_f32_16x16x32_bf16 v[178:181], v[222:225], v[204:207], v[0:3]
	s_setprio 0
	v_add3_u32 v18, s2, v190, v149
	s_barrier
	s_nop 0
	ds_read_b128 v[0:3], v18
	ds_read_b128 v[4:7], v18 offset:1024
	ds_read_b128 v[182:185], v18 offset:2048
	ds_read_b128 v[196:199], v18 offset:3072
	ds_read_b128 v[18:21], v250 offset:32768
	ds_read_b128 v[22:25], v250 offset:33792
	ds_read_b128 v[42:45], v251 offset:34816
	ds_read_b128 v[46:49], v251 offset:35840
	ds_read_b128 v[200:203], v251 offset:36864
	ds_read_b128 v[204:207], v251 offset:37888
	ds_read_b128 v[218:221], v251 offset:38912
	ds_read_b128 v[222:225], v251 offset:39936
	s_waitcnt vmcnt(2)
	s_barrier
	s_waitcnt lgkmcnt(0)
	s_setprio 1
	s_waitcnt lgkmcnt(0)
	v_mfma_f32_16x16x32_bf16 v[34:37], v[0:3], v[18:21], v[126:129]
	v_mfma_f32_16x16x32_bf16 v[110:113], v[4:7], v[22:25], v[34:37]
	v_mfma_f32_16x16x32_bf16 v[34:37], v[182:185], v[18:21], v[122:125]
	v_mfma_f32_16x16x32_bf16 v[106:109], v[196:199], v[22:25], v[34:37]
	v_mfma_f32_16x16x32_bf16 v[34:37], v[0:3], v[42:45], v[118:121]
	v_mfma_f32_16x16x32_bf16 v[90:93], v[4:7], v[46:49], v[34:37]
	v_mfma_f32_16x16x32_bf16 v[34:37], v[182:185], v[42:45], v[114:117]
	v_mfma_f32_16x16x32_bf16 v[86:89], v[196:199], v[46:49], v[34:37]
	v_mfma_f32_16x16x32_bf16 v[34:37], v[0:3], v[200:203], v[208:211]
	v_mfma_f32_16x16x32_bf16 v[62:65], v[4:7], v[204:207], v[34:37]
	v_mfma_f32_16x16x32_bf16 v[34:37], v[182:185], v[200:203], v[214:217]
	v_mfma_f32_16x16x32_bf16 v[58:61], v[196:199], v[204:207], v[34:37]
	v_mfma_f32_16x16x32_bf16 v[34:37], v[0:3], v[218:221], v[102:105]
	v_mfma_f32_16x16x32_bf16 v[38:41], v[4:7], v[222:225], v[34:37]
	v_mfma_f32_16x16x32_bf16 v[34:37], v[182:185], v[218:221], v[98:101]
	v_mfma_f32_16x16x32_bf16 v[34:37], v[196:199], v[222:225], v[34:37]
	s_setprio 0
	s_nop 0
	v_add3_u32 v98, s91, v190, v149
	s_barrier
	ds_read_b128 v[208:211], v98
	ds_read_b128 v[214:217], v98 offset:1024
	ds_read_b128 v[242:245], v98 offset:2048
	ds_read_b128 v[246:249], v98 offset:3072
	s_waitcnt vmcnt(0)
	s_barrier
	s_waitcnt lgkmcnt(0)
	s_setprio 1
	s_waitcnt lgkmcnt(0)
	v_mfma_f32_16x16x32_bf16 v[94:97], v[208:211], v[18:21], v[94:97]
	v_mfma_f32_16x16x32_bf16 v[18:21], v[242:245], v[18:21], v[166:169]
	v_mfma_f32_16x16x32_bf16 v[122:125], v[246:249], v[22:25], v[18:21]
	v_mfma_f32_16x16x32_bf16 v[18:21], v[208:211], v[42:45], v[170:173]
	v_mfma_f32_16x16x32_bf16 v[118:121], v[214:217], v[46:49], v[18:21]
	v_mfma_f32_16x16x32_bf16 v[18:21], v[242:245], v[42:45], v[82:85]
	v_mfma_f32_16x16x32_bf16 v[114:117], v[246:249], v[46:49], v[18:21]
	v_mfma_f32_16x16x32_bf16 v[18:21], v[208:211], v[200:203], v[78:81]
	v_mfma_f32_16x16x32_bf16 v[102:105], v[214:217], v[204:207], v[18:21]
	v_mfma_f32_16x16x32_bf16 v[18:21], v[242:245], v[200:203], v[74:77]
	v_mfma_f32_16x16x32_bf16 v[126:129], v[214:217], v[22:25], v[94:97]
	v_mfma_f32_16x16x32_bf16 v[94:97], v[246:249], v[204:207], v[18:21]
	v_mfma_f32_16x16x32_bf16 v[18:21], v[208:211], v[218:221], v[70:73]
	v_mfma_f32_16x16x32_bf16 v[70:73], v[214:217], v[222:225], v[18:21]
	v_mfma_f32_16x16x32_bf16 v[18:21], v[242:245], v[218:221], v[66:69]
	v_mfma_f32_16x16x32_bf16 v[66:69], v[246:249], v[222:225], v[18:21]
	s_setprio 0
	s_barrier
	ds_read_b128 v[82:85], v250 offset:49152
	ds_read_b128 v[166:169], v250 offset:50176
	ds_read_b128 v[170:173], v251 offset:51200
	ds_read_b128 v[200:203], v251 offset:52224
	ds_read_b128 v[204:207], v251 offset:53248
	ds_read_b128 v[218:221], v251 offset:54272
	ds_read_b128 v[222:225], v251 offset:55296
	ds_read_b128 v[250:253], v251 offset:56320
	s_barrier
	s_waitcnt lgkmcnt(0)
	s_setprio 1
	s_waitcnt lgkmcnt(0)
	v_mfma_f32_16x16x32_bf16 v[18:21], v[0:3], v[82:85], v[226:229]
	v_mfma_f32_16x16x32_bf16 v[78:81], v[4:7], v[166:169], v[18:21]
	v_mfma_f32_16x16x32_bf16 v[18:21], v[182:185], v[82:85], v[230:233]
	v_mfma_f32_16x16x32_bf16 v[74:77], v[196:199], v[166:169], v[18:21]
	v_mfma_f32_16x16x32_bf16 v[18:21], v[0:3], v[170:173], v[54:57]
	v_mfma_f32_16x16x32_bf16 v[46:49], v[4:7], v[200:203], v[18:21]
	v_mfma_f32_16x16x32_bf16 v[18:21], v[182:185], v[170:173], v[50:53]
	v_mfma_f32_16x16x32_bf16 v[42:45], v[196:199], v[200:203], v[18:21]
	v_mfma_f32_16x16x32_bf16 v[18:21], v[0:3], v[204:207], v[234:237]
	v_mfma_f32_16x16x32_bf16 v[0:3], v[0:3], v[222:225], v[150:153]
	v_mfma_f32_16x16x32_bf16 v[22:25], v[4:7], v[218:221], v[18:21]
	v_mfma_f32_16x16x32_bf16 v[18:21], v[182:185], v[204:207], v[238:241]
	v_mfma_f32_16x16x32_bf16 v[4:7], v[4:7], v[250:253], v[0:3]
	v_mfma_f32_16x16x32_bf16 v[0:3], v[182:185], v[222:225], v[154:157]
	v_mfma_f32_16x16x32_bf16 v[18:21], v[196:199], v[218:221], v[18:21]
	v_mfma_f32_16x16x32_bf16 v[0:3], v[196:199], v[250:253], v[0:3]
	s_setprio 0
	s_setprio 1
	v_mfma_f32_16x16x32_bf16 v[26:29], v[242:245], v[82:85], v[26:29]
	v_mfma_f32_16x16x32_bf16 v[30:33], v[208:211], v[82:85], v[30:33]
	v_mfma_f32_16x16x32_bf16 v[82:85], v[246:249], v[166:169], v[26:29]
	v_mfma_f32_16x16x32_bf16 v[26:29], v[208:211], v[170:173], v[158:161]
	v_mfma_f32_16x16x32_bf16 v[54:57], v[214:217], v[200:203], v[26:29]
	v_mfma_f32_16x16x32_bf16 v[26:29], v[242:245], v[170:173], v[162:165]
	v_mfma_f32_16x16x32_bf16 v[8:11], v[242:245], v[204:207], v[8:11]
	v_mfma_f32_16x16x32_bf16 v[50:53], v[246:249], v[200:203], v[26:29]
	v_mfma_f32_16x16x32_bf16 v[12:15], v[208:211], v[204:207], v[12:15]
	v_mfma_f32_16x16x32_bf16 v[26:29], v[246:249], v[218:221], v[8:11]
	v_mfma_f32_16x16x32_bf16 v[8:11], v[208:211], v[222:225], v[174:177]
	v_mfma_f32_16x16x32_bf16 v[98:101], v[214:217], v[166:169], v[30:33]
	v_mfma_f32_16x16x32_bf16 v[30:33], v[214:217], v[218:221], v[12:15]
	v_mfma_f32_16x16x32_bf16 v[12:15], v[214:217], v[250:253], v[8:11]
	v_mfma_f32_16x16x32_bf16 v[8:11], v[242:245], v[222:225], v[178:181]
	v_mfma_f32_16x16x32_bf16 v[8:11], v[246:249], v[250:253], v[8:11]
	s_setprio 0
	s_movk_i32 s1, 0x100
	v_cmp_gt_u32_e32 vcc, s1, v144
	s_barrier
	s_and_saveexec_b64 s[12:13], vcc
	s_cbranch_execz .LBB0_649
	s_barrier
